# BO3 + sliver 4-MFMA variants: chains adjacent, second chain k order flipped so the chain boundary shares the B operand
# baseline (speedup 1.0000x reference)
; #define PG8_SB(B) __builtin_amdgcn_rcpf(1.f + expneg(B))
; #define PG8_SB(B) __builtin_amdgcn_rcpf(1.f + expneg(B))
; #define PG8_STAGE(bufoff, gbase, voff) do { _Pragma("unroll") for (int _i = 0; _i < 2; ++_i) \
;         __builtin_amdgcn_global_load_lds((const unsigned*)((const char*)(gbase) + (size_t)_i * qstep + (voff)[0]), (PG8_LAS unsigned*)(lds + (bufoff) + ldsw + _i * 8192), 16, 0, 0); } while (0)
; #define PG8_LDA(dst, b, h) do { _Pragma("unroll") for (int m = 0; m < 4; ++m) _Pragma("unroll") for (int k = 0; k < 2; ++k) dst[m][k] = *(const PG8_LAS bf16x8*)(lds + PG8_SA(b, h) + aoff + m * 2048 + k * 1024); } while (0)
; template <class Epi, class Sched, bool ALIGN_EPI = false, bool SP2 = false, bool SLIVER = false>
; __device__ __forceinline__ void gemm_phase(PG8_LAS unsigned char* lds, const Gemm g, const Sched& S, const Epi& E) {
;     ...
;         const bool has_next = S.next(ui + 1, nxt);
;         const char* nA = has_next ? (const char*)g.A + (size_t)nxt.pm * tstep + Epi::k0(nxt.seg) * 2 : cA; const char* nB = has_next ? (const char*)g.Bt + (size_t)nxt.pn * tstep + Epi::k0(nxt.seg) * 2 : cB;
;         const char* nS = has_next ? (const char*)g.A + (size_t)S.srow0 * K * 2 + (size_t)nxt.pm * sstep + Epi::k0(nxt.seg) * 2 : cS;
;         for (int t = 0; t < nt; t += 2) {
;             const bool last = (t == nt - 2);
;             const char* a1 = cA + (size_t)(t + 1) * kstep;
;             const char* a2 = last ? nA : cA + (size_t)(t + 2) * kstep; const char* b2 = last ? nB : cB + (size_t)(t + 2) * kstep;
;             const char* a3 = a2 + kstep; const char* b3 = b2 + kstep;
;             const char* s1 = cS + (size_t)(t + 1) * kstep; const char* s2 = last ? nS : cS + (size_t)(t + 2) * kstep;
;             if (last && has_next) S.a_ready(nxt);
;             if constexpr (SP2) {
;             PG8_LDB(B0, 0, 0); PG8_LDB(B1, 0, 1); PG8_SCHED; PG8_LDA(At, 0, 0); PG8_STAGE(PG8_SA(1, 1), a1 + hstep, voffA); PG8_STAGE_S(1, s1);
;             PG8_WAIT_V89(); PG8_WAIT_L(0); PG8_BAR; PG8_MMA(0, 0, At, B0); PG8_MMA(0, 1, At, B1); PG8_BAR; PG8_SCHED;
;             PG8_LDA(At, 0, 1); PG8_LDS_S(0); PG8_STAGE(PG8_SB(0, 0), b2, voffB); PG8_STAGE(PG8_SB(0, 1), b2 + hstep, voffB); PG8_STAGE(PG8_SA(0, 0), a2, voffA);
;             PG8_WAIT_V89(); PG8_WAIT_L(0); PG8_BAR; PG8_MMA(1, 0, At, B0); PG8_MMA(1, 1, At, B1); PG8_MMA_S(); PG8_BAR; PG8_SCHED;
.LBB0_498:
	s_cmp_eq_u32 s66, s80
	s_cselect_b64 s[86:87], -1, 0
	s_add_u32 s40, s16, s80
	s_addc_u32 s41, s17, s81
	s_add_u32 s68, s40, 0x100
	s_addc_u32 s69, s41, 0
	s_and_b64 s[40:41], s[86:87], exec
	s_cselect_b32 s41, s55, s69
	s_cselect_b32 s40, s54, s68
	s_add_u32 s76, s12, s80
	s_addc_u32 s77, s13, s81
	s_add_i32 s78, 0, 0x10000
	s_and_b64 s[68:69], s[86:87], exec
	v_add_u32_e32 v138, s78, v239
	s_cselect_b32 s69, s83, s77
	s_cselect_b32 s68, s82, s76
	s_add_i32 s76, 0, 0x14000
	ds_read_b128 v[146:149], v138
	ds_read_b128 v[150:153], v138 offset:1024
	ds_read_b128 v[154:157], v138 offset:2048
	ds_read_b128 v[158:161], v138 offset:3072
	v_add_u32_e32 v138, s76, v239
	ds_read_b128 v[166:169], v138
	ds_read_b128 v[170:173], v138 offset:1024
	ds_read_b128 v[174:177], v138 offset:2048
	ds_read_b128 v[162:165], v138 offset:3072
	v_lshl_add_u64 v[208:209], v[188:189], 0, s[80:81]
	v_lshl_add_u64 v[224:225], v[208:209], 0, s[34:35]
	s_add_i32 m0, s96, 0xc000
	s_mov_b64 s[88:89], 0x120080
	ds_read_b128 v[138:141], v242
	ds_read_b128 v[142:145], v242 offset:1024
	ds_read_b128 v[180:183], v242 offset:2048
	ds_read_b128 v[184:187], v242 offset:3072
	ds_read_b128 v[192:195], v242 offset:4096
	ds_read_b128 v[196:199], v242 offset:5120
	ds_read_b128 v[200:203], v242 offset:6144
	ds_read_b128 v[220:223], v242 offset:7168
	global_load_lds_dwordx4 v[224:225], off
	v_lshl_add_u64 v[208:209], v[208:209], 0, s[88:89]
	s_add_i32 m0, s96, 0xe000
	s_nop 0
	global_load_lds_dwordx4 v[208:209], off
	v_lshl_add_u64 v[208:209], v[190:191], 0, s[80:81]
	s_add_i32 m0, s94, 0x20800
	s_nop 0
	global_load_lds_dword v[208:209], off
	s_waitcnt vmcnt(9)
	s_waitcnt lgkmcnt(0)
	s_setprio 1
	s_barrier
	v_mfma_f32_16x16x32_bf16 v[134:137], v[146:149], v[138:141], v[134:137]
	v_mfma_f32_16x16x32_bf16 v[134:137], v[150:153], v[142:145], v[134:137]
	v_mfma_f32_16x16x32_bf16 v[130:133], v[158:161], v[142:145], v[130:133]
	v_mfma_f32_16x16x32_bf16 v[130:133], v[154:157], v[138:141], v[130:133]
	v_mfma_f32_16x16x32_bf16 v[122:125], v[154:157], v[180:183], v[122:125]
	v_mfma_f32_16x16x32_bf16 v[122:125], v[158:161], v[184:187], v[122:125]
	v_mfma_f32_16x16x32_bf16 v[126:129], v[150:153], v[184:187], v[126:129]
	v_mfma_f32_16x16x32_bf16 v[126:129], v[146:149], v[180:183], v[126:129]
	v_mfma_f32_16x16x32_bf16 v[118:121], v[146:149], v[192:195], v[118:121]
	v_mfma_f32_16x16x32_bf16 v[118:121], v[150:153], v[196:199], v[118:121]
	v_mfma_f32_16x16x32_bf16 v[114:117], v[158:161], v[196:199], v[114:117]
	v_mfma_f32_16x16x32_bf16 v[114:117], v[154:157], v[192:195], v[114:117]
	v_mfma_f32_16x16x32_bf16 v[106:109], v[154:157], v[200:203], v[106:109]
	v_mfma_f32_16x16x32_bf16 v[106:109], v[158:161], v[220:223], v[106:109]
	v_mfma_f32_16x16x32_bf16 v[110:113], v[150:153], v[220:223], v[110:113]
	v_mfma_f32_16x16x32_bf16 v[110:113], v[146:149], v[200:203], v[110:113]
	s_setprio 0
	s_setprio 1
	v_mfma_f32_16x16x32_bf16 v[66:69], v[174:177], v[200:203], v[66:69]
	v_mfma_f32_16x16x32_bf16 v[66:69], v[162:165], v[220:223], v[66:69]
	v_mfma_f32_16x16x32_bf16 v[98:101], v[162:165], v[142:145], v[98:101]
	v_mfma_f32_16x16x32_bf16 v[98:101], v[174:177], v[138:141], v[98:101]
	v_mfma_f32_16x16x32_bf16 v[102:105], v[166:169], v[138:141], v[102:105]
	v_mfma_f32_16x16x32_bf16 v[102:105], v[170:173], v[142:145], v[102:105]
	v_mfma_f32_16x16x32_bf16 v[90:93], v[170:173], v[184:187], v[90:93]
	v_mfma_f32_16x16x32_bf16 v[90:93], v[166:169], v[180:183], v[90:93]
	v_mfma_f32_16x16x32_bf16 v[86:89], v[174:177], v[180:183], v[86:89]
	v_mfma_f32_16x16x32_bf16 v[86:89], v[162:165], v[184:187], v[86:89]
	v_mfma_f32_16x16x32_bf16 v[74:77], v[162:165], v[196:199], v[74:77]
	v_mfma_f32_16x16x32_bf16 v[74:77], v[174:177], v[192:195], v[74:77]
	v_mfma_f32_16x16x32_bf16 v[78:81], v[166:169], v[192:195], v[78:81]
	v_mfma_f32_16x16x32_bf16 v[78:81], v[170:173], v[196:199], v[78:81]
	v_mfma_f32_16x16x32_bf16 v[70:73], v[170:173], v[220:223], v[70:73]
	v_mfma_f32_16x16x32_bf16 v[70:73], v[166:169], v[200:203], v[70:73]
	s_barrier
	s_setprio 0
	s_add_i32 s77, 0, 0x20000
	v_lshl_add_u64 v[192:193], s[68:69], 0, v[212:213]
	s_add_i32 s68, s78, s95
	v_add_u32_e32 v178, s77, v240
	v_add_u32_e32 v184, s77, v241
	s_mov_b32 m0, s68
	s_mov_b64 s[88:89], 0x60000
	ds_read_b128 v[138:141], v242 offset:16384
	ds_read_b128 v[142:145], v242 offset:17408
	ds_read_b128 v[196:199], v242 offset:18432
	ds_read_b128 v[200:203], v242 offset:19456
	ds_read_b128 v[220:223], v242 offset:20480
	ds_read_b128 v[224:227], v242 offset:21504
	ds_read_b128 v[228:231], v242 offset:22528
	ds_read_b128 v[232:235], v242 offset:23552
	ds_read_b128 v[180:183], v178
	ds_read_b128 v[184:187], v184
	global_load_lds_dwordx4 v[192:193], off
	v_lshl_add_u64 v[194:195], v[192:193], 0, s[88:89]
	s_add_i32 m0, s68, 0x2000
	s_add_i32 s68, s76, s95
	global_load_lds_dwordx4 v[194:195], off
	v_lshl_add_u64 v[194:195], v[192:193], 0, s[24:25]
	s_mov_b32 m0, s68
	s_nop 0
	global_load_lds_dwordx4 v[194:195], off
	v_lshl_add_u64 v[194:195], v[192:193], 0, s[14:15]
	s_add_i32 m0, s68, 0x2000
	s_nop 0
	global_load_lds_dwordx4 v[194:195], off
	v_lshl_add_u64 v[194:195], s[40:41], 0, v[210:211]
	s_mov_b32 m0, s96
	v_lshl_add_u64 v[208:209], v[194:195], 0, s[88:89]
	global_load_lds_dwordx4 v[194:195], off
	s_mov_b32 m0, s19
	s_nop 0
	global_load_lds_dwordx4 v[208:209], off
	s_waitcnt vmcnt(9)
	s_waitcnt lgkmcnt(0)
	s_setprio 1
	s_barrier
; #define PG8_STAGE(bufoff, gbase, voff) do { _Pragma("unroll") for (int _i = 0; _i < 2; ++_i) \
;         __builtin_amdgcn_global_load_lds((const unsigned*)((const char*)(gbase) + (size_t)_i * qstep + (voff)[0]), (PG8_LAS unsigned*)(lds + (bufoff) + ldsw + _i * 8192), 16, 0, 0); } while (0)
; #define PG8_LDA(dst, b, h) do { _Pragma("unroll") for (int m = 0; m < 4; ++m) _Pragma("unroll") for (int k = 0; k < 2; ++k) dst[m][k] = *(const PG8_LAS bf16x8*)(lds + PG8_SA(b, h) + aoff + m * 2048 + k * 1024); } while (0)
; #define PG8_LDB(dst, b, h) do { _Pragma("unroll") for (int n = 0; n < 2; ++n) _Pragma("unroll") for (int k = 0; k < 2; ++k) dst[n][k] = *(const PG8_LAS bf16x8*)(lds + PG8_SB(b, h) + boff + n * 2048 + k * 1024); } while (0)
; #define PG8_MMA(ai, bj, At, Bt) do { __builtin_amdgcn_s_setprio(1); _Pragma("unroll") for (int m = 0; m < 4; ++m) _Pragma("unroll") for (int n = 0; n < 2; ++n) _Pragma("unroll") for (int k = 0; k < 2; ++k) \
;         acc[ai][bj][m][n] = __builtin_amdgcn_mfma_f32_16x16x32_bf16(Bt[n][k], At[m][k], acc[ai][bj][m][n], 0, 0, 0); __builtin_amdgcn_s_setprio(0); } while (0)
; #define PG8_WAIT_V89() do { if constexpr (SLIVER) PG8_WAIT_V(9); else PG8_WAIT_V(8); } while (0)
; #define PG8_STAGE_S(b, gbase) do { if constexpr (SLIVER) __builtin_amdgcn_global_load_lds((const unsigned*)((const char*)(gbase) + voffS), (PG8_LAS unsigned*)(lds + STAGE_BYTES + (b) * 2048 + wid * 256), 4, 0, 0); } while (0)
; #define PG8_WAIT_L(n) asm volatile("s_waitcnt lgkmcnt(" #n ")" ::: "memory")
; #define PG8_BAR __builtin_amdgcn_s_barrier()
; #define PG8_SCHED __builtin_amdgcn_sched_barrier(0)
; template <class Epi, class Sched, bool ALIGN_EPI = false, bool SP2 = false, bool SLIVER = false>
; __device__ __forceinline__ void gemm_phase(PG8_LAS unsigned char* lds, const Gemm g, const Sched& S, const Epi& E) {
;     ...
;             PG8_WAIT_V89(); PG8_WAIT_L(0); PG8_BAR; PG8_MMA(1, 0, At, B0); PG8_MMA(1, 1, At, B1); PG8_MMA_S(); PG8_BAR; PG8_SCHED;
;             PG8_LDB(B0, 1, 0); PG8_LDB(B1, 1, 1); PG8_SCHED; PG8_LDA(At, 1, 0); PG8_STAGE(PG8_SA(0, 1), a2 + hstep, voffA); PG8_STAGE_S(0, s2);
;             PG8_WAIT_V89(); PG8_WAIT_L(0); PG8_BAR; PG8_MMA(0, 0, At, B0); PG8_MMA(0, 1, At, B1); PG8_BAR; PG8_SCHED;
	v_mfma_f32_16x16x32_bf16 v[62:65], v[146:149], v[138:141], v[62:65]
	v_mfma_f32_16x16x32_bf16 v[62:65], v[150:153], v[142:145], v[62:65]
	v_mfma_f32_16x16x32_bf16 v[58:61], v[158:161], v[142:145], v[58:61]
	v_mfma_f32_16x16x32_bf16 v[58:61], v[154:157], v[138:141], v[58:61]
	v_mfma_f32_16x16x32_bf16 v[50:53], v[154:157], v[196:199], v[50:53]
	v_mfma_f32_16x16x32_bf16 v[50:53], v[158:161], v[200:203], v[50:53]
	v_mfma_f32_16x16x32_bf16 v[54:57], v[150:153], v[200:203], v[54:57]
	v_mfma_f32_16x16x32_bf16 v[54:57], v[146:149], v[196:199], v[54:57]
	v_mfma_f32_16x16x32_bf16 v[46:49], v[146:149], v[220:223], v[46:49]
	v_mfma_f32_16x16x32_bf16 v[46:49], v[150:153], v[224:227], v[46:49]
	v_mfma_f32_16x16x32_bf16 v[42:45], v[158:161], v[224:227], v[42:45]
	v_mfma_f32_16x16x32_bf16 v[42:45], v[154:157], v[220:223], v[42:45]
	v_mfma_f32_16x16x32_bf16 v[34:37], v[154:157], v[228:231], v[34:37]
	v_mfma_f32_16x16x32_bf16 v[34:37], v[158:161], v[232:235], v[34:37]
	v_mfma_f32_16x16x32_bf16 v[38:41], v[150:153], v[232:235], v[38:41]
	v_mfma_f32_16x16x32_bf16 v[38:41], v[146:149], v[228:231], v[38:41]
	s_setprio 0
	s_setprio 1
	v_mfma_f32_16x16x32_bf16 v[2:5], v[174:177], v[228:231], v[2:5]
	v_mfma_f32_16x16x32_bf16 v[2:5], v[162:165], v[232:235], v[2:5]
	v_mfma_f32_16x16x32_bf16 v[26:29], v[162:165], v[142:145], v[26:29]
	v_mfma_f32_16x16x32_bf16 v[26:29], v[174:177], v[138:141], v[26:29]
	v_mfma_f32_16x16x32_bf16 v[30:33], v[166:169], v[138:141], v[30:33]
	v_mfma_f32_16x16x32_bf16 v[30:33], v[170:173], v[142:145], v[30:33]
	v_mfma_f32_16x16x32_bf16 v[22:25], v[170:173], v[200:203], v[22:25]
	v_mfma_f32_16x16x32_bf16 v[22:25], v[166:169], v[196:199], v[22:25]
	v_mfma_f32_16x16x32_bf16 v[18:21], v[174:177], v[196:199], v[18:21]
	v_mfma_f32_16x16x32_bf16 v[18:21], v[162:165], v[200:203], v[18:21]
	v_mfma_f32_16x16x32_bf16 v[10:13], v[162:165], v[224:227], v[10:13]
	v_mfma_f32_16x16x32_bf16 v[10:13], v[174:177], v[220:223], v[10:13]
	v_mfma_f32_16x16x32_bf16 v[14:17], v[166:169], v[220:223], v[14:17]
	v_mfma_f32_16x16x32_bf16 v[14:17], v[170:173], v[224:227], v[14:17]
	v_mfma_f32_16x16x32_bf16 v[6:9], v[170:173], v[232:235], v[6:9]
	v_mfma_f32_16x16x32_bf16 v[6:9], v[166:169], v[228:231], v[6:9]
	s_setprio 0
	s_setprio 1
	s_and_b64 vcc, exec, s[52:53]
	s_cbranch_vccz .Lslv_b0
	v_mfma_f32_16x16x32_bf16 v[138:141], v[166:169], v[180:183], v[82:85]
	v_mfma_f32_16x16x32_bf16 v[138:141], v[170:173], v[184:187], v[138:141]
	v_mfma_f32_16x16x32_bf16 v[142:145], v[162:165], v[184:187], v[94:97]
	v_mfma_f32_16x16x32_bf16 v[142:145], v[174:177], v[180:183], v[142:145]
	s_branch .LBB0_502
.LBB0_500:
.Lslv_b0:
	v_mfma_f32_16x16x32_bf16 v[82:85], v[146:149], v[180:183], v[82:85]
	v_mfma_f32_16x16x32_bf16 v[138:141], v[150:153], v[184:187], v[82:85]
	v_mfma_f32_16x16x32_bf16 v[82:85], v[158:161], v[184:187], v[94:97]
	v_mfma_f32_16x16x32_bf16 v[142:145], v[154:157], v[180:183], v[82:85]
.LBB0_502:
	s_barrier
	s_setprio 0
	s_add_u32 s68, s62, s80
	s_addc_u32 s69, s63, s81
	s_add_u32 s76, s68, 0x100
	s_addc_u32 s77, s69, 0
	s_and_b64 s[68:69], s[86:87], exec
	s_cselect_b32 s69, s85, s77
	s_cselect_b32 s68, s84, s76
	s_add_i32 s76, 0, 0x18000
	v_add_u32_e32 v82, s76, v239
	s_add_i32 s77, 0, 0x1c000
	ds_read_b128 v[146:149], v82
	ds_read_b128 v[150:153], v82 offset:1024
	ds_read_b128 v[154:157], v82 offset:2048
	ds_read_b128 v[158:161], v82 offset:3072
	v_add_u32_e32 v82, s77, v239
	ds_read_b128 v[166:169], v82
	ds_read_b128 v[170:173], v82 offset:1024
	ds_read_b128 v[174:177], v82 offset:2048
	ds_read_b128 v[162:165], v82 offset:3072
	s_mov_b32 m0, s91
	v_lshl_add_u64 v[208:209], v[194:195], 0, s[24:25]
	ds_read_b128 v[82:85], v242 offset:32768
	ds_read_b128 v[94:97], v242 offset:33792
	ds_read_b128 v[180:183], v242 offset:34816
	ds_read_b128 v[184:187], v242 offset:35840
	ds_read_b128 v[196:199], v242 offset:36864
	ds_read_b128 v[200:203], v242 offset:37888
	ds_read_b128 v[220:223], v242 offset:38912
	ds_read_b128 v[224:227], v242 offset:39936
	global_load_lds_dwordx4 v[208:209], off
	v_lshl_add_u64 v[208:209], v[194:195], 0, s[14:15]
	s_mov_b32 m0, s92
	s_nop 0
	global_load_lds_dwordx4 v[208:209], off
	v_lshl_add_u64 v[208:209], s[68:69], 0, v[214:215]
	s_mov_b32 m0, s93
	s_nop 0
	global_load_lds_dword v[208:209], off
	s_waitcnt vmcnt(9)
	s_waitcnt lgkmcnt(0)
	s_setprio 1
	s_barrier
; #define PG8_SB(B) __builtin_amdgcn_rcpf(1.f + expneg(B))
; #define PG8_SB(B) __builtin_amdgcn_rcpf(1.f + expneg(B))
; #define PG8_STAGE(bufoff, gbase, voff) do { _Pragma("unroll") for (int _i = 0; _i < 2; ++_i) \
;         __builtin_amdgcn_global_load_lds((const unsigned*)((const char*)(gbase) + (size_t)_i * qstep + (voff)[0]), (PG8_LAS unsigned*)(lds + (bufoff) + ldsw + _i * 8192), 16, 0, 0); } while (0)
; #define PG8_LDA(dst, b, h) do { _Pragma("unroll") for (int m = 0; m < 4; ++m) _Pragma("unroll") for (int k = 0; k < 2; ++k) dst[m][k] = *(const PG8_LAS bf16x8*)(lds + PG8_SA(b, h) + aoff + m * 2048 + k * 1024); } while (0)
; #define PG8_MMA(ai, bj, At, Bt) do { __builtin_amdgcn_s_setprio(1); _Pragma("unroll") for (int m = 0; m < 4; ++m) _Pragma("unroll") for (int n = 0; n < 2; ++n) _Pragma("unroll") for (int k = 0; k < 2; ++k) \
;         acc[ai][bj][m][n] = __builtin_amdgcn_mfma_f32_16x16x32_bf16(Bt[n][k], At[m][k], acc[ai][bj][m][n], 0, 0, 0); __builtin_amdgcn_s_setprio(0); } while (0)
; #define PG8_WAIT_V89() do { if constexpr (SLIVER) PG8_WAIT_V(9); else PG8_WAIT_V(8); } while (0)
; #define PG8_LDS_S(b) do { if constexpr (SLIVER) { Sf[0] = *(const PG8_LAS bf16x8*)(lds + STAGE_BYTES + (b) * 2048 + soff0); Sf[1] = *(const PG8_LAS bf16x8*)(lds + STAGE_BYTES + (b) * 2048 + (soff0 ^ 64)); } } while (0)
; #define PG8_WAIT_L(n) asm volatile("s_waitcnt lgkmcnt(" #n ")" ::: "memory")
; #define PG8_BAR __builtin_amdgcn_s_barrier()
; #define PG8_SCHED __builtin_amdgcn_sched_barrier(0)
; template <class Epi, class Sched, bool ALIGN_EPI = false, bool SP2 = false, bool SLIVER = false>
; __device__ __forceinline__ void gemm_phase(PG8_LAS unsigned char* lds, const Gemm g, const Sched& S, const Epi& E) {
;     ...
;             PG8_WAIT_V89(); PG8_WAIT_L(0); PG8_BAR; PG8_MMA(0, 0, At, B0); PG8_MMA(0, 1, At, B1); PG8_BAR; PG8_SCHED;
;             PG8_LDA(At, 1, 1); PG8_LDS_S(1); PG8_STAGE(PG8_SB(1, 0), b3, voffB); PG8_STAGE(PG8_SB(1, 1), b3 + hstep, voffB); PG8_STAGE(PG8_SA(1, 0), a3, voffA);
;             PG8_WAIT_V89(); PG8_WAIT_L(0); PG8_BAR; PG8_MMA(1, 0, At, B0); PG8_MMA(1, 1, At, B1); PG8_MMA_S(); PG8_BAR; PG8_SCHED;
	v_mfma_f32_16x16x32_bf16 v[134:137], v[146:149], v[82:85], v[134:137]
	v_mfma_f32_16x16x32_bf16 v[134:137], v[150:153], v[94:97], v[134:137]
	v_mfma_f32_16x16x32_bf16 v[130:133], v[158:161], v[94:97], v[130:133]
	v_mfma_f32_16x16x32_bf16 v[130:133], v[154:157], v[82:85], v[130:133]
	v_mfma_f32_16x16x32_bf16 v[122:125], v[154:157], v[180:183], v[122:125]
	v_mfma_f32_16x16x32_bf16 v[122:125], v[158:161], v[184:187], v[122:125]
	v_mfma_f32_16x16x32_bf16 v[126:129], v[150:153], v[184:187], v[126:129]
	v_mfma_f32_16x16x32_bf16 v[126:129], v[146:149], v[180:183], v[126:129]
	v_mfma_f32_16x16x32_bf16 v[118:121], v[146:149], v[196:199], v[118:121]
	v_mfma_f32_16x16x32_bf16 v[118:121], v[150:153], v[200:203], v[118:121]
	v_mfma_f32_16x16x32_bf16 v[114:117], v[158:161], v[200:203], v[114:117]
	v_mfma_f32_16x16x32_bf16 v[114:117], v[154:157], v[196:199], v[114:117]
	v_mfma_f32_16x16x32_bf16 v[106:109], v[154:157], v[220:223], v[106:109]
	v_mfma_f32_16x16x32_bf16 v[106:109], v[158:161], v[224:227], v[106:109]
	v_mfma_f32_16x16x32_bf16 v[110:113], v[150:153], v[224:227], v[110:113]
	v_mfma_f32_16x16x32_bf16 v[110:113], v[146:149], v[220:223], v[110:113]
	s_setprio 0
	s_setprio 1
	v_mfma_f32_16x16x32_bf16 v[102:105], v[166:169], v[82:85], v[102:105]
	v_mfma_f32_16x16x32_bf16 v[102:105], v[170:173], v[94:97], v[102:105]
	v_mfma_f32_16x16x32_bf16 v[82:85], v[174:177], v[82:85], v[98:101]
	v_mfma_f32_16x16x32_bf16 v[98:101], v[162:165], v[94:97], v[82:85]
	v_mfma_f32_16x16x32_bf16 v[82:85], v[166:169], v[180:183], v[90:93]
	v_mfma_f32_16x16x32_bf16 v[90:93], v[170:173], v[184:187], v[82:85]
	v_mfma_f32_16x16x32_bf16 v[82:85], v[174:177], v[180:183], v[86:89]
	v_mfma_f32_16x16x32_bf16 v[86:89], v[162:165], v[184:187], v[82:85]
	v_mfma_f32_16x16x32_bf16 v[78:81], v[166:169], v[196:199], v[78:81]
	v_mfma_f32_16x16x32_bf16 v[78:81], v[170:173], v[200:203], v[78:81]
	v_mfma_f32_16x16x32_bf16 v[74:77], v[174:177], v[196:199], v[74:77]
	v_mfma_f32_16x16x32_bf16 v[74:77], v[162:165], v[200:203], v[74:77]
	v_mfma_f32_16x16x32_bf16 v[70:73], v[166:169], v[220:223], v[70:73]
	v_mfma_f32_16x16x32_bf16 v[70:73], v[170:173], v[224:227], v[70:73]
	v_mfma_f32_16x16x32_bf16 v[66:69], v[174:177], v[220:223], v[66:69]
	v_mfma_f32_16x16x32_bf16 v[66:69], v[162:165], v[224:227], v[66:69]
	s_barrier
	s_setprio 0
	s_add_i32 s68, 0, 0x20800
	v_add_u32_e32 v178, s68, v240
	v_add_u32_e32 v184, s68, v241
	s_add_i32 s68, s76, s95
	v_lshl_add_u64 v[208:209], v[192:193], 0, s[26:27]
	s_mov_b32 m0, s68
	ds_read_b128 v[82:85], v242 offset:49152
	ds_read_b128 v[94:97], v242 offset:50176
	ds_read_b128 v[196:199], v242 offset:51200
	ds_read_b128 v[200:203], v242 offset:52224
	ds_read_b128 v[220:223], v242 offset:53248
	ds_read_b128 v[224:227], v242 offset:54272
	ds_read_b128 v[228:231], v242 offset:55296
	ds_read_b128 v[232:235], v242 offset:56320
	ds_read_b128 v[180:183], v178
	ds_read_b128 v[184:187], v184
	global_load_lds_dwordx4 v[208:209], off
	v_lshl_add_u64 v[208:209], v[192:193], 0, s[72:73]
	s_add_i32 m0, s68, 0x2000
	s_add_i32 s68, s77, s95
	global_load_lds_dwordx4 v[208:209], off
	v_lshl_add_u64 v[208:209], v[192:193], 0, s[34:35]
	s_mov_b32 m0, s68
	s_mov_b64 s[76:77], 0x120080
	global_load_lds_dwordx4 v[208:209], off
	v_lshl_add_u64 v[192:193], v[192:193], 0, s[76:77]
	s_add_i32 m0, s68, 0x2000
	s_nop 0
	global_load_lds_dwordx4 v[192:193], off
	v_lshl_add_u64 v[192:193], v[194:195], 0, s[26:27]
	s_mov_b32 m0, s97
	s_nop 0
	global_load_lds_dwordx4 v[192:193], off
	v_lshl_add_u64 v[192:193], v[194:195], 0, s[72:73]
	s_mov_b32 m0, s18
	s_nop 0
	global_load_lds_dwordx4 v[192:193], off
	s_waitcnt vmcnt(9)
	s_waitcnt lgkmcnt(0)
	s_setprio 1
	s_barrier
	v_mfma_f32_16x16x32_bf16 v[62:65], v[146:149], v[82:85], v[62:65]
	v_mfma_f32_16x16x32_bf16 v[62:65], v[150:153], v[94:97], v[62:65]
	v_mfma_f32_16x16x32_bf16 v[58:61], v[158:161], v[94:97], v[58:61]
	v_mfma_f32_16x16x32_bf16 v[58:61], v[154:157], v[82:85], v[58:61]
	v_mfma_f32_16x16x32_bf16 v[50:53], v[154:157], v[196:199], v[50:53]
	v_mfma_f32_16x16x32_bf16 v[50:53], v[158:161], v[200:203], v[50:53]
	v_mfma_f32_16x16x32_bf16 v[54:57], v[150:153], v[200:203], v[54:57]
	v_mfma_f32_16x16x32_bf16 v[54:57], v[146:149], v[196:199], v[54:57]
	v_mfma_f32_16x16x32_bf16 v[46:49], v[146:149], v[220:223], v[46:49]
	v_mfma_f32_16x16x32_bf16 v[46:49], v[150:153], v[224:227], v[46:49]
	v_mfma_f32_16x16x32_bf16 v[42:45], v[158:161], v[224:227], v[42:45]
	v_mfma_f32_16x16x32_bf16 v[42:45], v[154:157], v[220:223], v[42:45]
	v_mfma_f32_16x16x32_bf16 v[34:37], v[154:157], v[228:231], v[34:37]
	v_mfma_f32_16x16x32_bf16 v[34:37], v[158:161], v[232:235], v[34:37]
	v_mfma_f32_16x16x32_bf16 v[38:41], v[150:153], v[232:235], v[38:41]
	v_mfma_f32_16x16x32_bf16 v[38:41], v[146:149], v[228:231], v[38:41]
	s_setprio 0
	s_setprio 1
	v_mfma_f32_16x16x32_bf16 v[2:5], v[174:177], v[228:231], v[2:5]
	v_mfma_f32_16x16x32_bf16 v[2:5], v[162:165], v[232:235], v[2:5]
	v_mfma_f32_16x16x32_bf16 v[26:29], v[162:165], v[94:97], v[26:29]
	v_mfma_f32_16x16x32_bf16 v[26:29], v[174:177], v[82:85], v[26:29]
	v_mfma_f32_16x16x32_bf16 v[30:33], v[166:169], v[82:85], v[30:33]
	v_mfma_f32_16x16x32_bf16 v[30:33], v[170:173], v[94:97], v[30:33]
	v_mfma_f32_16x16x32_bf16 v[22:25], v[170:173], v[200:203], v[22:25]
	v_mfma_f32_16x16x32_bf16 v[22:25], v[166:169], v[196:199], v[22:25]
	v_mfma_f32_16x16x32_bf16 v[18:21], v[174:177], v[196:199], v[18:21]
	v_mfma_f32_16x16x32_bf16 v[18:21], v[162:165], v[200:203], v[18:21]
	v_mfma_f32_16x16x32_bf16 v[10:13], v[162:165], v[224:227], v[10:13]
	v_mfma_f32_16x16x32_bf16 v[10:13], v[174:177], v[220:223], v[10:13]
	v_mfma_f32_16x16x32_bf16 v[14:17], v[166:169], v[220:223], v[14:17]
	v_mfma_f32_16x16x32_bf16 v[14:17], v[170:173], v[224:227], v[14:17]
	v_mfma_f32_16x16x32_bf16 v[6:9], v[170:173], v[232:235], v[6:9]
	v_mfma_f32_16x16x32_bf16 v[6:9], v[166:169], v[228:231], v[6:9]
	s_setprio 0
	s_setprio 1
	s_and_b64 vcc, exec, s[52:53]
	s_cbranch_vccz .Lslv_c0
	v_mfma_f32_16x16x32_bf16 v[82:85], v[166:169], v[180:183], v[138:141]
	v_mfma_f32_16x16x32_bf16 v[82:85], v[170:173], v[184:187], v[82:85]
	v_mfma_f32_16x16x32_bf16 v[94:97], v[162:165], v[184:187], v[142:145]
	v_mfma_f32_16x16x32_bf16 v[94:97], v[174:177], v[180:183], v[94:97]
	s_branch .LBB0_497
.LBB0_504:
.Lslv_c0:
	v_mfma_f32_16x16x32_bf16 v[82:85], v[146:149], v[180:183], v[138:141]
	v_mfma_f32_16x16x32_bf16 v[82:85], v[150:153], v[184:187], v[82:85]
	v_mfma_f32_16x16x32_bf16 v[94:97], v[158:161], v[184:187], v[142:145]
	v_mfma_f32_16x16x32_bf16 v[94:97], v[154:157], v[180:183], v[94:97]
	s_branch .LBB0_497

; #define PG8_SB(B) __builtin_amdgcn_rcpf(1.f + expneg(B))
; #define PG8_SB(B) __builtin_amdgcn_rcpf(1.f + expneg(B))
; #define PG8_STAGE(bufoff, gbase, voff) do { _Pragma("unroll") for (int _i = 0; _i < 2; ++_i) \
;         __builtin_amdgcn_global_load_lds((const unsigned*)((const char*)(gbase) + (size_t)_i * qstep + (voff)[0]), (PG8_LAS unsigned*)(lds + (bufoff) + ldsw + _i * 8192), 16, 0, 0); } while (0)
; #define PG8_LDA(dst, b, h) do { _Pragma("unroll") for (int m = 0; m < 4; ++m) _Pragma("unroll") for (int k = 0; k < 2; ++k) dst[m][k] = *(const PG8_LAS bf16x8*)(lds + PG8_SA(b, h) + aoff + m * 2048 + k * 1024); } while (0)
; template <class Epi, class Sched, bool ALIGN_EPI = false, bool SP2 = false, bool SLIVER = false>
; __device__ __forceinline__ void gemm_phase(PG8_LAS unsigned char* lds, const Gemm g, const Sched& S, const Epi& E) {
;     ...
;         const bool has_next = S.next(ui + 1, nxt);
;         const char* nA = has_next ? (const char*)g.A + (size_t)nxt.pm * tstep + Epi::k0(nxt.seg) * 2 : cA; const char* nB = has_next ? (const char*)g.Bt + (size_t)nxt.pn * tstep + Epi::k0(nxt.seg) * 2 : cB;
;         const char* nS = has_next ? (const char*)g.A + (size_t)S.srow0 * K * 2 + (size_t)nxt.pm * sstep + Epi::k0(nxt.seg) * 2 : cS;
;         for (int t = 0; t < nt; t += 2) {
;             const bool last = (t == nt - 2);
;             const char* a1 = cA + (size_t)(t + 1) * kstep;
;             const char* a2 = last ? nA : cA + (size_t)(t + 2) * kstep; const char* b2 = last ? nB : cB + (size_t)(t + 2) * kstep;
;             const char* a3 = a2 + kstep; const char* b3 = b2 + kstep;
;             const char* s1 = cS + (size_t)(t + 1) * kstep; const char* s2 = last ? nS : cS + (size_t)(t + 2) * kstep;
;             if (last && has_next) S.a_ready(nxt);
;             if constexpr (SP2) {
;             PG8_LDB(B0, 0, 0); PG8_LDB(B1, 0, 1); PG8_SCHED; PG8_LDA(At, 0, 0); PG8_STAGE(PG8_SA(1, 1), a1 + hstep, voffA); PG8_STAGE_S(1, s1);
;             PG8_WAIT_V89(); PG8_WAIT_L(0); PG8_BAR; PG8_MMA(0, 0, At, B0); PG8_MMA(0, 1, At, B1); PG8_BAR; PG8_SCHED;
;             PG8_LDA(At, 0, 1); PG8_LDS_S(0); PG8_STAGE(PG8_SB(0, 0), b2, voffB); PG8_STAGE(PG8_SB(0, 1), b2 + hstep, voffB); PG8_STAGE(PG8_SA(0, 0), a2, voffA);
;             PG8_WAIT_V89(); PG8_WAIT_L(0); PG8_BAR; PG8_MMA(1, 0, At, B0); PG8_MMA(1, 1, At, B1); PG8_MMA_S(); PG8_BAR; PG8_SCHED;
.LBB0_598:
	s_add_u32 s40, s92, s62
	s_addc_u32 s41, s93, s63
	s_add_u32 s77, s40, 0x100
	s_addc_u32 s78, s41, 0
	s_add_u32 s83, s68, s62
	s_addc_u32 s79, s69, s63
	s_add_i32 s96, 0, 0x10000
	s_cmpk_eq_i32 s62, 0xf00
	s_cselect_b64 s[80:81], -1, 0
	s_and_b64 s[40:41], s[80:81], exec
	s_cselect_b32 s41, s12, s78
	s_cselect_b32 s40, s13, s77
	v_add_u32_e32 v138, s96, v212
	s_cselect_b32 s79, s17, s79
	s_cselect_b32 s78, s55, s83
	s_add_i32 s77, 0, 0x14000
	ds_read_b128 v[146:149], v138
	ds_read_b128 v[150:153], v138 offset:1024
	ds_read_b128 v[154:157], v138 offset:2048
	ds_read_b128 v[158:161], v138 offset:3072
	v_add_u32_e32 v138, s77, v212
	ds_read_b128 v[166:169], v138
	ds_read_b128 v[170:173], v138 offset:1024
	ds_read_b128 v[174:177], v138 offset:2048
	ds_read_b128 v[162:165], v138 offset:3072
	v_lshl_add_u64 v[202:203], v[200:201], 0, s[62:63]
	v_lshl_add_u64 v[208:209], v[202:203], 0, s[30:31]
	s_add_i32 m0, s85, 0xc000
	ds_read_b128 v[138:141], v215
	ds_read_b128 v[142:145], v215 offset:1024
	ds_read_b128 v[180:183], v215 offset:2048
	ds_read_b128 v[184:187], v215 offset:3072
	ds_read_b128 v[216:219], v215 offset:4096
	ds_read_b128 v[220:223], v215 offset:5120
	ds_read_b128 v[224:227], v215 offset:6144
	ds_read_b128 v[228:231], v215 offset:7168
	global_load_lds_dwordx4 v[208:209], off
	v_lshl_add_u64 v[202:203], v[202:203], 0, s[34:35]
	s_add_i32 m0, s85, 0xe000
	s_nop 0
	global_load_lds_dwordx4 v[202:203], off
	v_lshl_add_u64 v[202:203], v[198:199], 0, s[62:63]
	s_add_i32 m0, s45, 0x20800
	s_nop 0
	global_load_lds_dword v[202:203], off
	s_waitcnt vmcnt(9)
	s_waitcnt lgkmcnt(0)
	s_setprio 1
	s_barrier
	v_mfma_f32_16x16x32_bf16 v[134:137], v[146:149], v[138:141], v[134:137]
	v_mfma_f32_16x16x32_bf16 v[134:137], v[150:153], v[142:145], v[134:137]
	v_mfma_f32_16x16x32_bf16 v[130:133], v[158:161], v[142:145], v[130:133]
	v_mfma_f32_16x16x32_bf16 v[130:133], v[154:157], v[138:141], v[130:133]
	v_mfma_f32_16x16x32_bf16 v[114:117], v[154:157], v[180:183], v[114:117]
	v_mfma_f32_16x16x32_bf16 v[114:117], v[158:161], v[184:187], v[114:117]
	v_mfma_f32_16x16x32_bf16 v[118:121], v[150:153], v[184:187], v[118:121]
	v_mfma_f32_16x16x32_bf16 v[118:121], v[146:149], v[180:183], v[118:121]
	v_mfma_f32_16x16x32_bf16 v[102:105], v[146:149], v[216:219], v[102:105]
	v_mfma_f32_16x16x32_bf16 v[102:105], v[150:153], v[220:223], v[102:105]
	v_mfma_f32_16x16x32_bf16 v[98:101], v[158:161], v[220:223], v[98:101]
	v_mfma_f32_16x16x32_bf16 v[98:101], v[154:157], v[216:219], v[98:101]
	v_mfma_f32_16x16x32_bf16 v[82:85], v[154:157], v[224:227], v[82:85]
	v_mfma_f32_16x16x32_bf16 v[82:85], v[158:161], v[228:231], v[82:85]
	v_mfma_f32_16x16x32_bf16 v[86:89], v[150:153], v[228:231], v[86:89]
	v_mfma_f32_16x16x32_bf16 v[86:89], v[146:149], v[224:227], v[86:89]
	s_setprio 0
	s_setprio 1
	v_mfma_f32_16x16x32_bf16 v[74:77], v[174:177], v[224:227], v[74:77]
	v_mfma_f32_16x16x32_bf16 v[74:77], v[162:165], v[228:231], v[74:77]
	v_mfma_f32_16x16x32_bf16 v[122:125], v[162:165], v[142:145], v[122:125]
	v_mfma_f32_16x16x32_bf16 v[122:125], v[174:177], v[138:141], v[122:125]
	v_mfma_f32_16x16x32_bf16 v[126:129], v[166:169], v[138:141], v[126:129]
	v_mfma_f32_16x16x32_bf16 v[126:129], v[170:173], v[142:145], v[126:129]
	v_mfma_f32_16x16x32_bf16 v[110:113], v[170:173], v[184:187], v[110:113]
	v_mfma_f32_16x16x32_bf16 v[110:113], v[166:169], v[180:183], v[110:113]
	v_mfma_f32_16x16x32_bf16 v[106:109], v[174:177], v[180:183], v[106:109]
	v_mfma_f32_16x16x32_bf16 v[106:109], v[162:165], v[184:187], v[106:109]
	v_mfma_f32_16x16x32_bf16 v[90:93], v[162:165], v[220:223], v[90:93]
	v_mfma_f32_16x16x32_bf16 v[90:93], v[174:177], v[216:219], v[90:93]
	v_mfma_f32_16x16x32_bf16 v[94:97], v[166:169], v[216:219], v[94:97]
	v_mfma_f32_16x16x32_bf16 v[94:97], v[170:173], v[220:223], v[94:97]
	v_mfma_f32_16x16x32_bf16 v[78:81], v[170:173], v[228:231], v[78:81]
	v_mfma_f32_16x16x32_bf16 v[78:81], v[166:169], v[224:227], v[78:81]
	s_barrier
	s_setprio 0
	s_add_i32 s83, 0, 0x20000
	v_lshl_add_u64 v[202:203], s[78:79], 0, v[190:191]
	s_add_i32 s78, s96, s18
	v_add_u32_e32 v178, s83, v213
	v_add_u32_e32 v184, s83, v214
	s_mov_b32 m0, s78
	ds_read_b128 v[138:141], v215 offset:16384
	ds_read_b128 v[142:145], v215 offset:17408
	ds_read_b128 v[216:219], v215 offset:18432
	ds_read_b128 v[220:223], v215 offset:19456
	ds_read_b128 v[224:227], v215 offset:20480
	ds_read_b128 v[228:231], v215 offset:21504
	ds_read_b128 v[232:235], v215 offset:22528
	ds_read_b128 v[240:243], v215 offset:23552
	ds_read_b128 v[180:183], v178
	ds_read_b128 v[184:187], v184
	global_load_lds_dwordx4 v[202:203], off
	v_lshl_add_u64 v[208:209], v[202:203], 0, s[20:21]
	s_add_i32 m0, s78, 0x2000
	s_add_i32 s77, s77, s18
	global_load_lds_dwordx4 v[208:209], off
	v_lshl_add_u64 v[208:209], v[202:203], 0, s[22:23]
	s_mov_b32 m0, s77
	v_lshl_add_u64 v[210:211], s[40:41], 0, v[188:189]
	global_load_lds_dwordx4 v[208:209], off
	v_lshl_add_u64 v[208:209], v[202:203], 0, s[24:25]
	s_add_i32 m0, s77, 0x2000
	s_nop 0
	global_load_lds_dwordx4 v[208:209], off
	s_mov_b32 m0, s85
	v_lshl_add_u64 v[208:209], v[210:211], 0, s[20:21]
	global_load_lds_dwordx4 v[210:211], off
	s_mov_b32 m0, s19
	s_nop 0
	global_load_lds_dwordx4 v[208:209], off
	s_waitcnt vmcnt(9)
	s_waitcnt lgkmcnt(0)
	s_setprio 1
	s_barrier
; #define PG8_STAGE(bufoff, gbase, voff) do { _Pragma("unroll") for (int _i = 0; _i < 2; ++_i) \
;         __builtin_amdgcn_global_load_lds((const unsigned*)((const char*)(gbase) + (size_t)_i * qstep + (voff)[0]), (PG8_LAS unsigned*)(lds + (bufoff) + ldsw + _i * 8192), 16, 0, 0); } while (0)
; #define PG8_LDA(dst, b, h) do { _Pragma("unroll") for (int m = 0; m < 4; ++m) _Pragma("unroll") for (int k = 0; k < 2; ++k) dst[m][k] = *(const PG8_LAS bf16x8*)(lds + PG8_SA(b, h) + aoff + m * 2048 + k * 1024); } while (0)
; #define PG8_LDB(dst, b, h) do { _Pragma("unroll") for (int n = 0; n < 2; ++n) _Pragma("unroll") for (int k = 0; k < 2; ++k) dst[n][k] = *(const PG8_LAS bf16x8*)(lds + PG8_SB(b, h) + boff + n * 2048 + k * 1024); } while (0)
; #define PG8_MMA(ai, bj, At, Bt) do { __builtin_amdgcn_s_setprio(1); _Pragma("unroll") for (int m = 0; m < 4; ++m) _Pragma("unroll") for (int n = 0; n < 2; ++n) _Pragma("unroll") for (int k = 0; k < 2; ++k) \
;         acc[ai][bj][m][n] = __builtin_amdgcn_mfma_f32_16x16x32_bf16(Bt[n][k], At[m][k], acc[ai][bj][m][n], 0, 0, 0); __builtin_amdgcn_s_setprio(0); } while (0)
; #define PG8_WAIT_V89() do { if constexpr (SLIVER) PG8_WAIT_V(9); else PG8_WAIT_V(8); } while (0)
; #define PG8_STAGE_S(b, gbase) do { if constexpr (SLIVER) __builtin_amdgcn_global_load_lds((const unsigned*)((const char*)(gbase) + voffS), (PG8_LAS unsigned*)(lds + STAGE_BYTES + (b) * 2048 + wid * 256), 4, 0, 0); } while (0)
; #define PG8_WAIT_L(n) asm volatile("s_waitcnt lgkmcnt(" #n ")" ::: "memory")
; #define PG8_BAR __builtin_amdgcn_s_barrier()
; #define PG8_SCHED __builtin_amdgcn_sched_barrier(0)
; template <class Epi, class Sched, bool ALIGN_EPI = false, bool SP2 = false, bool SLIVER = false>
; __device__ __forceinline__ void gemm_phase(PG8_LAS unsigned char* lds, const Gemm g, const Sched& S, const Epi& E) {
;     ...
;             PG8_WAIT_V89(); PG8_WAIT_L(0); PG8_BAR; PG8_MMA(1, 0, At, B0); PG8_MMA(1, 1, At, B1); PG8_MMA_S(); PG8_BAR; PG8_SCHED;
;             PG8_LDB(B0, 1, 0); PG8_LDB(B1, 1, 1); PG8_SCHED; PG8_LDA(At, 1, 0); PG8_STAGE(PG8_SA(0, 1), a2 + hstep, voffA); PG8_STAGE_S(0, s2);
;             PG8_WAIT_V89(); PG8_WAIT_L(0); PG8_BAR; PG8_MMA(0, 0, At, B0); PG8_MMA(0, 1, At, B1); PG8_BAR; PG8_SCHED;
	v_mfma_f32_16x16x32_bf16 v[70:73], v[146:149], v[138:141], v[70:73]
	v_mfma_f32_16x16x32_bf16 v[70:73], v[150:153], v[142:145], v[70:73]
	v_mfma_f32_16x16x32_bf16 v[66:69], v[158:161], v[142:145], v[66:69]
	v_mfma_f32_16x16x32_bf16 v[66:69], v[154:157], v[138:141], v[66:69]
	v_mfma_f32_16x16x32_bf16 v[50:53], v[154:157], v[216:219], v[50:53]
	v_mfma_f32_16x16x32_bf16 v[50:53], v[158:161], v[220:223], v[50:53]
	v_mfma_f32_16x16x32_bf16 v[54:57], v[150:153], v[220:223], v[54:57]
	v_mfma_f32_16x16x32_bf16 v[54:57], v[146:149], v[216:219], v[54:57]
	v_mfma_f32_16x16x32_bf16 v[38:41], v[146:149], v[224:227], v[38:41]
	v_mfma_f32_16x16x32_bf16 v[38:41], v[150:153], v[228:231], v[38:41]
	v_mfma_f32_16x16x32_bf16 v[34:37], v[158:161], v[228:231], v[34:37]
	v_mfma_f32_16x16x32_bf16 v[34:37], v[154:157], v[224:227], v[34:37]
	v_mfma_f32_16x16x32_bf16 v[18:21], v[154:157], v[232:235], v[18:21]
	v_mfma_f32_16x16x32_bf16 v[18:21], v[158:161], v[240:243], v[18:21]
	v_mfma_f32_16x16x32_bf16 v[22:25], v[150:153], v[240:243], v[22:25]
	v_mfma_f32_16x16x32_bf16 v[22:25], v[146:149], v[232:235], v[22:25]
	s_setprio 0
	s_setprio 1
	v_mfma_f32_16x16x32_bf16 v[10:13], v[174:177], v[232:235], v[10:13]
	v_mfma_f32_16x16x32_bf16 v[10:13], v[162:165], v[240:243], v[10:13]
	v_mfma_f32_16x16x32_bf16 v[58:61], v[162:165], v[142:145], v[58:61]
	v_mfma_f32_16x16x32_bf16 v[58:61], v[174:177], v[138:141], v[58:61]
	v_mfma_f32_16x16x32_bf16 v[62:65], v[166:169], v[138:141], v[62:65]
	v_mfma_f32_16x16x32_bf16 v[62:65], v[170:173], v[142:145], v[62:65]
	v_mfma_f32_16x16x32_bf16 v[46:49], v[170:173], v[220:223], v[46:49]
	v_mfma_f32_16x16x32_bf16 v[46:49], v[166:169], v[216:219], v[46:49]
	v_mfma_f32_16x16x32_bf16 v[42:45], v[174:177], v[216:219], v[42:45]
	v_mfma_f32_16x16x32_bf16 v[42:45], v[162:165], v[220:223], v[42:45]
	v_mfma_f32_16x16x32_bf16 v[26:29], v[162:165], v[228:231], v[26:29]
	v_mfma_f32_16x16x32_bf16 v[26:29], v[174:177], v[224:227], v[26:29]
	v_mfma_f32_16x16x32_bf16 v[30:33], v[166:169], v[224:227], v[30:33]
	v_mfma_f32_16x16x32_bf16 v[30:33], v[170:173], v[228:231], v[30:33]
	v_mfma_f32_16x16x32_bf16 v[14:17], v[170:173], v[240:243], v[14:17]
	v_mfma_f32_16x16x32_bf16 v[14:17], v[166:169], v[232:235], v[14:17]
	s_setprio 0
	s_setprio 1
	s_and_b64 vcc, exec, s[52:53]
	s_cbranch_vccz .Lslv_b1
	v_mfma_f32_16x16x32_bf16 v[138:141], v[166:169], v[180:183], v[6:9]
	v_mfma_f32_16x16x32_bf16 v[138:141], v[170:173], v[184:187], v[138:141]
	v_mfma_f32_16x16x32_bf16 v[142:145], v[162:165], v[184:187], v[2:5]
	v_mfma_f32_16x16x32_bf16 v[142:145], v[174:177], v[180:183], v[142:145]
	s_branch .LBB0_602
.LBB0_600:
.Lslv_b1:
	v_mfma_f32_16x16x32_bf16 v[6:9], v[146:149], v[180:183], v[6:9]
	v_mfma_f32_16x16x32_bf16 v[138:141], v[150:153], v[184:187], v[6:9]
	v_mfma_f32_16x16x32_bf16 v[2:5], v[158:161], v[184:187], v[2:5]
	v_mfma_f32_16x16x32_bf16 v[142:145], v[154:157], v[180:183], v[2:5]
.LBB0_602:
	s_barrier
	s_setprio 0
	s_add_u32 s77, s94, s62
	s_addc_u32 s78, s95, s63
	s_add_u32 s77, s77, 0x100
	s_addc_u32 s83, s78, 0
	s_and_b64 s[78:79], s[80:81], exec
	s_cselect_b32 s79, s66, s83
	s_cselect_b32 s78, s67, s77
	s_add_i32 s77, 0, 0x18000
	v_add_u32_e32 v2, s77, v212
	s_add_i32 s80, 0, 0x1c000
	ds_read_b128 v[146:149], v2
	ds_read_b128 v[150:153], v2 offset:1024
	ds_read_b128 v[154:157], v2 offset:2048
	ds_read_b128 v[158:161], v2 offset:3072
	v_add_u32_e32 v2, s80, v212
	ds_read_b128 v[166:169], v2
	ds_read_b128 v[170:173], v2 offset:1024
	ds_read_b128 v[174:177], v2 offset:2048
	ds_read_b128 v[162:165], v2 offset:3072
	s_mov_b32 m0, s49
	v_lshl_add_u64 v[208:209], v[210:211], 0, s[22:23]
	ds_read_b128 v[2:5], v215 offset:32768
	ds_read_b128 v[6:9], v215 offset:33792
	ds_read_b128 v[180:183], v215 offset:34816
	ds_read_b128 v[184:187], v215 offset:35840
	ds_read_b128 v[216:219], v215 offset:36864
	ds_read_b128 v[220:223], v215 offset:37888
	ds_read_b128 v[224:227], v215 offset:38912
	ds_read_b128 v[228:231], v215 offset:39936
	global_load_lds_dwordx4 v[208:209], off
	v_lshl_add_u64 v[208:209], v[210:211], 0, s[24:25]
	s_mov_b32 m0, s50
	s_nop 0
	global_load_lds_dwordx4 v[208:209], off
	v_lshl_add_u64 v[208:209], s[78:79], 0, v[192:193]
	s_mov_b32 m0, s51
	s_nop 0
	global_load_lds_dword v[208:209], off
	s_waitcnt vmcnt(9)
	s_waitcnt lgkmcnt(0)
	s_setprio 1
	s_barrier
; #define PG8_SB(B) __builtin_amdgcn_rcpf(1.f + expneg(B))
; #define PG8_SB(B) __builtin_amdgcn_rcpf(1.f + expneg(B))
; #define PG8_STAGE(bufoff, gbase, voff) do { _Pragma("unroll") for (int _i = 0; _i < 2; ++_i) \
;         __builtin_amdgcn_global_load_lds((const unsigned*)((const char*)(gbase) + (size_t)_i * qstep + (voff)[0]), (PG8_LAS unsigned*)(lds + (bufoff) + ldsw + _i * 8192), 16, 0, 0); } while (0)
; #define PG8_LDA(dst, b, h) do { _Pragma("unroll") for (int m = 0; m < 4; ++m) _Pragma("unroll") for (int k = 0; k < 2; ++k) dst[m][k] = *(const PG8_LAS bf16x8*)(lds + PG8_SA(b, h) + aoff + m * 2048 + k * 1024); } while (0)
; #define PG8_MMA(ai, bj, At, Bt) do { __builtin_amdgcn_s_setprio(1); _Pragma("unroll") for (int m = 0; m < 4; ++m) _Pragma("unroll") for (int n = 0; n < 2; ++n) _Pragma("unroll") for (int k = 0; k < 2; ++k) \
;         acc[ai][bj][m][n] = __builtin_amdgcn_mfma_f32_16x16x32_bf16(Bt[n][k], At[m][k], acc[ai][bj][m][n], 0, 0, 0); __builtin_amdgcn_s_setprio(0); } while (0)
; #define PG8_WAIT_V89() do { if constexpr (SLIVER) PG8_WAIT_V(9); else PG8_WAIT_V(8); } while (0)
; #define PG8_LDS_S(b) do { if constexpr (SLIVER) { Sf[0] = *(const PG8_LAS bf16x8*)(lds + STAGE_BYTES + (b) * 2048 + soff0); Sf[1] = *(const PG8_LAS bf16x8*)(lds + STAGE_BYTES + (b) * 2048 + (soff0 ^ 64)); } } while (0)
; #define PG8_WAIT_L(n) asm volatile("s_waitcnt lgkmcnt(" #n ")" ::: "memory")
; #define PG8_BAR __builtin_amdgcn_s_barrier()
; #define PG8_SCHED __builtin_amdgcn_sched_barrier(0)
; template <class Epi, class Sched, bool ALIGN_EPI = false, bool SP2 = false, bool SLIVER = false>
; __device__ __forceinline__ void gemm_phase(PG8_LAS unsigned char* lds, const Gemm g, const Sched& S, const Epi& E) {
;     ...
;             PG8_WAIT_V89(); PG8_WAIT_L(0); PG8_BAR; PG8_MMA(0, 0, At, B0); PG8_MMA(0, 1, At, B1); PG8_BAR; PG8_SCHED;
;             PG8_LDA(At, 1, 1); PG8_LDS_S(1); PG8_STAGE(PG8_SB(1, 0), b3, voffB); PG8_STAGE(PG8_SB(1, 1), b3 + hstep, voffB); PG8_STAGE(PG8_SA(1, 0), a3, voffA);
;             PG8_WAIT_V89(); PG8_WAIT_L(0); PG8_BAR; PG8_MMA(1, 0, At, B0); PG8_MMA(1, 1, At, B1); PG8_MMA_S(); PG8_BAR; PG8_SCHED;
	v_mfma_f32_16x16x32_bf16 v[134:137], v[146:149], v[2:5], v[134:137]
	v_mfma_f32_16x16x32_bf16 v[134:137], v[150:153], v[6:9], v[134:137]
	v_mfma_f32_16x16x32_bf16 v[130:133], v[158:161], v[6:9], v[130:133]
	v_mfma_f32_16x16x32_bf16 v[130:133], v[154:157], v[2:5], v[130:133]
	v_mfma_f32_16x16x32_bf16 v[114:117], v[154:157], v[180:183], v[114:117]
	v_mfma_f32_16x16x32_bf16 v[114:117], v[158:161], v[184:187], v[114:117]
	v_mfma_f32_16x16x32_bf16 v[118:121], v[150:153], v[184:187], v[118:121]
	v_mfma_f32_16x16x32_bf16 v[118:121], v[146:149], v[180:183], v[118:121]
	v_mfma_f32_16x16x32_bf16 v[102:105], v[146:149], v[216:219], v[102:105]
	v_mfma_f32_16x16x32_bf16 v[102:105], v[150:153], v[220:223], v[102:105]
	v_mfma_f32_16x16x32_bf16 v[98:101], v[158:161], v[220:223], v[98:101]
	v_mfma_f32_16x16x32_bf16 v[98:101], v[154:157], v[216:219], v[98:101]
	v_mfma_f32_16x16x32_bf16 v[82:85], v[154:157], v[224:227], v[82:85]
	v_mfma_f32_16x16x32_bf16 v[82:85], v[158:161], v[228:231], v[82:85]
	v_mfma_f32_16x16x32_bf16 v[86:89], v[150:153], v[228:231], v[86:89]
	v_mfma_f32_16x16x32_bf16 v[86:89], v[146:149], v[224:227], v[86:89]
	s_setprio 0
	s_setprio 1
	v_mfma_f32_16x16x32_bf16 v[126:129], v[166:169], v[2:5], v[126:129]
	v_mfma_f32_16x16x32_bf16 v[126:129], v[170:173], v[6:9], v[126:129]
	v_mfma_f32_16x16x32_bf16 v[2:5], v[174:177], v[2:5], v[122:125]
	v_mfma_f32_16x16x32_bf16 v[122:125], v[162:165], v[6:9], v[2:5]
	v_mfma_f32_16x16x32_bf16 v[2:5], v[166:169], v[180:183], v[110:113]
	v_mfma_f32_16x16x32_bf16 v[110:113], v[170:173], v[184:187], v[2:5]
	v_mfma_f32_16x16x32_bf16 v[2:5], v[174:177], v[180:183], v[106:109]
	v_mfma_f32_16x16x32_bf16 v[106:109], v[162:165], v[184:187], v[2:5]
	v_mfma_f32_16x16x32_bf16 v[2:5], v[166:169], v[216:219], v[94:97]
	v_mfma_f32_16x16x32_bf16 v[94:97], v[170:173], v[220:223], v[2:5]
	v_mfma_f32_16x16x32_bf16 v[2:5], v[174:177], v[216:219], v[90:93]
	v_mfma_f32_16x16x32_bf16 v[90:93], v[162:165], v[220:223], v[2:5]
	v_mfma_f32_16x16x32_bf16 v[2:5], v[166:169], v[224:227], v[78:81]
	v_mfma_f32_16x16x32_bf16 v[78:81], v[170:173], v[228:231], v[2:5]
	v_mfma_f32_16x16x32_bf16 v[2:5], v[174:177], v[224:227], v[74:77]
	v_mfma_f32_16x16x32_bf16 v[74:77], v[162:165], v[228:231], v[2:5]
	s_barrier
	s_setprio 0
	s_add_i32 s78, 0, 0x20800
	s_add_i32 s77, s77, s18
	v_add_u32_e32 v178, s78, v213
	v_add_u32_e32 v184, s78, v214
	v_lshl_add_u64 v[208:209], v[202:203], 0, s[26:27]
	s_mov_b32 m0, s77
	ds_read_b128 v[2:5], v215 offset:49152
	ds_read_b128 v[6:9], v215 offset:50176
	ds_read_b128 v[216:219], v215 offset:51200
	ds_read_b128 v[220:223], v215 offset:52224
	ds_read_b128 v[224:227], v215 offset:53248
	ds_read_b128 v[228:231], v215 offset:54272
	ds_read_b128 v[232:235], v215 offset:55296
	ds_read_b128 v[240:243], v215 offset:56320
	ds_read_b128 v[180:183], v178
	ds_read_b128 v[184:187], v184
	global_load_lds_dwordx4 v[208:209], off
	v_lshl_add_u64 v[208:209], v[202:203], 0, s[28:29]
	s_add_i32 m0, s77, 0x2000
	s_add_i32 s77, s80, s18
	global_load_lds_dwordx4 v[208:209], off
	v_lshl_add_u64 v[208:209], v[202:203], 0, s[30:31]
	s_mov_b32 m0, s77
	v_lshl_add_u64 v[202:203], v[202:203], 0, s[34:35]
	global_load_lds_dwordx4 v[208:209], off
	s_add_i32 m0, s77, 0x2000
	s_nop 0
	global_load_lds_dwordx4 v[202:203], off
	v_lshl_add_u64 v[202:203], v[210:211], 0, s[26:27]
	s_mov_b32 m0, s10
	s_nop 0
	global_load_lds_dwordx4 v[202:203], off
	v_lshl_add_u64 v[202:203], v[210:211], 0, s[28:29]
	s_mov_b32 m0, s2
	s_nop 0
	global_load_lds_dwordx4 v[202:203], off
	s_waitcnt vmcnt(9)
	s_waitcnt lgkmcnt(0)
	s_setprio 1
	s_barrier
	v_mfma_f32_16x16x32_bf16 v[70:73], v[146:149], v[2:5], v[70:73]
	v_mfma_f32_16x16x32_bf16 v[70:73], v[150:153], v[6:9], v[70:73]
	v_mfma_f32_16x16x32_bf16 v[66:69], v[158:161], v[6:9], v[66:69]
	v_mfma_f32_16x16x32_bf16 v[66:69], v[154:157], v[2:5], v[66:69]
	v_mfma_f32_16x16x32_bf16 v[50:53], v[154:157], v[216:219], v[50:53]
	v_mfma_f32_16x16x32_bf16 v[50:53], v[158:161], v[220:223], v[50:53]
	v_mfma_f32_16x16x32_bf16 v[54:57], v[150:153], v[220:223], v[54:57]
	v_mfma_f32_16x16x32_bf16 v[54:57], v[146:149], v[216:219], v[54:57]
	v_mfma_f32_16x16x32_bf16 v[38:41], v[146:149], v[224:227], v[38:41]
	v_mfma_f32_16x16x32_bf16 v[38:41], v[150:153], v[228:231], v[38:41]
	v_mfma_f32_16x16x32_bf16 v[34:37], v[158:161], v[228:231], v[34:37]
	v_mfma_f32_16x16x32_bf16 v[34:37], v[154:157], v[224:227], v[34:37]
	v_mfma_f32_16x16x32_bf16 v[18:21], v[154:157], v[232:235], v[18:21]
	v_mfma_f32_16x16x32_bf16 v[18:21], v[158:161], v[240:243], v[18:21]
	v_mfma_f32_16x16x32_bf16 v[22:25], v[150:153], v[240:243], v[22:25]
	v_mfma_f32_16x16x32_bf16 v[22:25], v[146:149], v[232:235], v[22:25]
	s_setprio 0
	s_setprio 1
	v_mfma_f32_16x16x32_bf16 v[62:65], v[166:169], v[2:5], v[62:65]
	v_mfma_f32_16x16x32_bf16 v[62:65], v[170:173], v[6:9], v[62:65]
	v_mfma_f32_16x16x32_bf16 v[2:5], v[174:177], v[2:5], v[58:61]
	v_mfma_f32_16x16x32_bf16 v[58:61], v[162:165], v[6:9], v[2:5]
	v_mfma_f32_16x16x32_bf16 v[2:5], v[166:169], v[216:219], v[46:49]
	v_mfma_f32_16x16x32_bf16 v[46:49], v[170:173], v[220:223], v[2:5]
	v_mfma_f32_16x16x32_bf16 v[2:5], v[174:177], v[216:219], v[42:45]
	v_mfma_f32_16x16x32_bf16 v[42:45], v[162:165], v[220:223], v[2:5]
	v_mfma_f32_16x16x32_bf16 v[2:5], v[166:169], v[224:227], v[30:33]
	v_mfma_f32_16x16x32_bf16 v[30:33], v[170:173], v[228:231], v[2:5]
	v_mfma_f32_16x16x32_bf16 v[2:5], v[174:177], v[224:227], v[26:29]
	v_mfma_f32_16x16x32_bf16 v[26:29], v[162:165], v[228:231], v[2:5]
	v_mfma_f32_16x16x32_bf16 v[2:5], v[166:169], v[232:235], v[14:17]
	v_mfma_f32_16x16x32_bf16 v[14:17], v[170:173], v[240:243], v[2:5]
	v_mfma_f32_16x16x32_bf16 v[2:5], v[174:177], v[232:235], v[10:13]
	v_mfma_f32_16x16x32_bf16 v[10:13], v[162:165], v[240:243], v[2:5]
	s_setprio 0
	s_setprio 1
	s_and_b64 vcc, exec, s[52:53]
	s_cbranch_vccz .Lslv_c1
	v_mfma_f32_16x16x32_bf16 v[2:5], v[166:169], v[180:183], v[138:141]
	v_mfma_f32_16x16x32_bf16 v[6:9], v[170:173], v[184:187], v[2:5]
	v_mfma_f32_16x16x32_bf16 v[2:5], v[162:165], v[184:187], v[142:145]
	v_mfma_f32_16x16x32_bf16 v[2:5], v[174:177], v[180:183], v[2:5]
	s_branch .LBB0_597
.LBB0_604:
.Lslv_c1:
	v_mfma_f32_16x16x32_bf16 v[2:5], v[146:149], v[180:183], v[138:141]
	v_mfma_f32_16x16x32_bf16 v[6:9], v[150:153], v[184:187], v[2:5]
	v_mfma_f32_16x16x32_bf16 v[2:5], v[158:161], v[184:187], v[142:145]
	v_mfma_f32_16x16x32_bf16 v[2:5], v[154:157], v[180:183], v[2:5]
	s_branch .LBB0_597

; #define PG8_SB(B) __builtin_amdgcn_rcpf(1.f + expneg(B))
; #define PG8_SB(B) __builtin_amdgcn_rcpf(1.f + expneg(B))
; #define PG8_STAGE(bufoff, gbase, voff) do { _Pragma("unroll") for (int _i = 0; _i < 2; ++_i) \
;         __builtin_amdgcn_global_load_lds((const unsigned*)((const char*)(gbase) + (size_t)_i * qstep + (voff)[0]), (PG8_LAS unsigned*)(lds + (bufoff) + ldsw + _i * 8192), 16, 0, 0); } while (0)
; #define PG8_LDA(dst, b, h) do { _Pragma("unroll") for (int m = 0; m < 4; ++m) _Pragma("unroll") for (int k = 0; k < 2; ++k) dst[m][k] = *(const PG8_LAS bf16x8*)(lds + PG8_SA(b, h) + aoff + m * 2048 + k * 1024); } while (0)
; template <class Epi, class Sched, bool ALIGN_EPI = false, bool SP2 = false, bool SLIVER = false>
; __device__ __forceinline__ void gemm_phase(PG8_LAS unsigned char* lds, const Gemm g, const Sched& S, const Epi& E) {
;     ...
;         const bool has_next = S.next(ui + 1, nxt);
;         const char* nA = has_next ? (const char*)g.A + (size_t)nxt.pm * tstep + Epi::k0(nxt.seg) * 2 : cA; const char* nB = has_next ? (const char*)g.Bt + (size_t)nxt.pn * tstep + Epi::k0(nxt.seg) * 2 : cB;
;         const char* nS = has_next ? (const char*)g.A + (size_t)S.srow0 * K * 2 + (size_t)nxt.pm * sstep + Epi::k0(nxt.seg) * 2 : cS;
;         for (int t = 0; t < nt; t += 2) {
;             const bool last = (t == nt - 2);
;             const char* a1 = cA + (size_t)(t + 1) * kstep;
;             const char* a2 = last ? nA : cA + (size_t)(t + 2) * kstep; const char* b2 = last ? nB : cB + (size_t)(t + 2) * kstep;
;             const char* a3 = a2 + kstep; const char* b3 = b2 + kstep;
;             const char* s1 = cS + (size_t)(t + 1) * kstep; const char* s2 = last ? nS : cS + (size_t)(t + 2) * kstep;
;             if (last && has_next) S.a_ready(nxt);
;             if constexpr (SP2) {
;             PG8_LDB(B0, 0, 0); PG8_LDB(B1, 0, 1); PG8_SCHED; PG8_LDA(At, 0, 0); PG8_STAGE(PG8_SA(1, 1), a1 + hstep, voffA); PG8_STAGE_S(1, s1);
;             PG8_WAIT_V89(); PG8_WAIT_L(0); PG8_BAR; PG8_MMA(0, 0, At, B0); PG8_MMA(0, 1, At, B1); PG8_BAR; PG8_SCHED;
;             PG8_LDA(At, 0, 1); PG8_LDS_S(0); PG8_STAGE(PG8_SB(0, 0), b2, voffB); PG8_STAGE(PG8_SB(0, 1), b2 + hstep, voffB); PG8_STAGE(PG8_SA(0, 0), a2, voffA);
;             PG8_WAIT_V89(); PG8_WAIT_L(0); PG8_BAR; PG8_MMA(1, 0, At, B0); PG8_MMA(1, 1, At, B1); PG8_MMA_S(); PG8_BAR; PG8_SCHED;
.LBB0_811:
	s_add_u32 s13, s90, s62
	s_addc_u32 s40, s91, s63
	s_add_u32 s13, s13, 0x100
	s_addc_u32 s66, s40, 0
	s_add_u32 s68, s2, s62
	s_addc_u32 s67, s3, s63
	s_add_i32 s69, 0, 0x10000
	s_cmpk_eq_i32 s62, 0x2b00
	s_cselect_b64 s[80:81], -1, 0
	s_and_b64 s[40:41], s[80:81], exec
	s_cselect_b32 s41, s85, s66
	s_cselect_b32 s40, s84, s13
	v_add_u32_e32 v66, s69, v220
	s_cselect_b32 s67, s87, s67
	s_cselect_b32 s66, s86, s68
	s_add_i32 s13, 0, 0x14000
	ds_read_b128 v[154:157], v66
	ds_read_b128 v[158:161], v66 offset:1024
	ds_read_b128 v[162:165], v66 offset:2048
	ds_read_b128 v[174:177], v66 offset:3072
	v_add_u32_e32 v66, s13, v220
	ds_read_b128 v[184:187], v66
	ds_read_b128 v[188:191], v66 offset:1024
	ds_read_b128 v[192:195], v66 offset:2048
	ds_read_b128 v[180:183], v66 offset:3072
	v_lshl_add_u64 v[146:147], v[214:215], 0, s[62:63]
	v_lshl_add_u64 v[148:149], v[146:147], 0, s[8:9]
	s_add_i32 m0, s19, 0xc000
	s_mov_b64 s[94:95], 0x210080
	ds_read_b128 v[66:69], v223
	ds_read_b128 v[70:73], v223 offset:1024
	ds_read_b128 v[74:77], v223 offset:2048
	ds_read_b128 v[78:81], v223 offset:3072
	ds_read_b128 v[216:219], v223 offset:4096
	ds_read_b128 v[224:227], v223 offset:5120
	ds_read_b128 v[228:231], v223 offset:6144
	ds_read_b128 v[232:235], v223 offset:7168
	global_load_lds_dwordx4 v[148:149], off
	v_lshl_add_u64 v[146:147], v[146:147], 0, s[94:95]
	s_add_i32 m0, s19, 0xe000
	s_nop 0
	global_load_lds_dwordx4 v[146:147], off
	v_lshl_add_u64 v[146:147], v[212:213], 0, s[62:63]
	s_add_i32 m0, s96, 0x20800
	s_nop 0
	global_load_lds_dword v[146:147], off
	s_waitcnt vmcnt(9)
	s_waitcnt lgkmcnt(0)
	s_setprio 1
	s_barrier
	v_mfma_f32_16x16x32_bf16 v[146:149], v[154:157], v[66:69], v[170:173]
	v_mfma_f32_16x16x32_bf16 v[146:149], v[158:161], v[70:73], v[146:149]
	v_mfma_f32_16x16x32_bf16 v[150:153], v[162:165], v[66:69], v[166:169]
	v_mfma_f32_16x16x32_bf16 v[150:153], v[174:177], v[70:73], v[150:153]
	v_mfma_f32_16x16x32_bf16 v[134:137], v[154:157], v[74:77], v[134:137]
	v_mfma_f32_16x16x32_bf16 v[134:137], v[158:161], v[78:81], v[134:137]
	v_mfma_f32_16x16x32_bf16 v[130:133], v[162:165], v[74:77], v[130:133]
	v_mfma_f32_16x16x32_bf16 v[130:133], v[174:177], v[78:81], v[130:133]
	v_mfma_f32_16x16x32_bf16 v[118:121], v[154:157], v[216:219], v[118:121]
	v_mfma_f32_16x16x32_bf16 v[118:121], v[158:161], v[224:227], v[118:121]
	v_mfma_f32_16x16x32_bf16 v[114:117], v[162:165], v[216:219], v[114:117]
	v_mfma_f32_16x16x32_bf16 v[114:117], v[174:177], v[224:227], v[114:117]
	v_mfma_f32_16x16x32_bf16 v[102:105], v[154:157], v[228:231], v[102:105]
	v_mfma_f32_16x16x32_bf16 v[102:105], v[158:161], v[232:235], v[102:105]
	v_mfma_f32_16x16x32_bf16 v[98:101], v[162:165], v[228:231], v[98:101]
	v_mfma_f32_16x16x32_bf16 v[98:101], v[174:177], v[232:235], v[98:101]
	s_setprio 0
	s_setprio 1
	v_mfma_f32_16x16x32_bf16 v[142:145], v[184:187], v[66:69], v[142:145]
	v_mfma_f32_16x16x32_bf16 v[142:145], v[188:191], v[70:73], v[142:145]
	v_mfma_f32_16x16x32_bf16 v[66:69], v[192:195], v[66:69], v[138:141]
	v_mfma_f32_16x16x32_bf16 v[138:141], v[180:183], v[70:73], v[66:69]
	v_mfma_f32_16x16x32_bf16 v[66:69], v[184:187], v[74:77], v[126:129]
	v_mfma_f32_16x16x32_bf16 v[126:129], v[188:191], v[78:81], v[66:69]
	v_mfma_f32_16x16x32_bf16 v[66:69], v[192:195], v[74:77], v[122:125]
	v_mfma_f32_16x16x32_bf16 v[122:125], v[180:183], v[78:81], v[66:69]
	v_mfma_f32_16x16x32_bf16 v[66:69], v[184:187], v[216:219], v[110:113]
	v_mfma_f32_16x16x32_bf16 v[110:113], v[188:191], v[224:227], v[66:69]
	v_mfma_f32_16x16x32_bf16 v[66:69], v[192:195], v[216:219], v[106:109]
	v_mfma_f32_16x16x32_bf16 v[106:109], v[180:183], v[224:227], v[66:69]
	v_mfma_f32_16x16x32_bf16 v[66:69], v[184:187], v[228:231], v[94:97]
	v_mfma_f32_16x16x32_bf16 v[94:97], v[188:191], v[232:235], v[66:69]
	v_mfma_f32_16x16x32_bf16 v[66:69], v[192:195], v[228:231], v[90:93]
	v_mfma_f32_16x16x32_bf16 v[90:93], v[180:183], v[232:235], v[66:69]
	s_barrier
	s_setprio 0
	s_add_i32 s68, 0, 0x20000
	v_lshl_add_u64 v[216:217], s[66:67], 0, v[198:199]
	s_add_i32 s66, s69, s18
	v_add_u32_e32 v74, s68, v221
	v_add_u32_e32 v75, s68, v222
	s_mov_b32 m0, s66
	ds_read_b128 v[66:69], v223 offset:16384
	ds_read_b128 v[70:73], v223 offset:17408
	ds_read_b128 v[224:227], v223 offset:18432
	ds_read_b128 v[228:231], v223 offset:19456
	ds_read_b128 v[232:235], v223 offset:20480
	ds_read_b128 v[240:243], v223 offset:21504
	ds_read_b128 v[244:247], v223 offset:22528
	ds_read_b128 v[248:251], v223 offset:23552
	ds_read_b128 v[166:169], v74
	ds_read_b128 v[170:173], v75
	global_load_lds_dwordx4 v[216:217], off
	v_lshl_add_u64 v[74:75], v[216:217], 0, s[64:65]
	s_add_i32 m0, s66, 0x2000
	s_add_i32 s13, s13, s18
	global_load_lds_dwordx4 v[74:75], off
	v_lshl_add_u64 v[74:75], v[216:217], 0, s[0:1]
	s_mov_b32 m0, s13
	v_lshl_add_u64 v[218:219], s[40:41], 0, v[196:197]
	global_load_lds_dwordx4 v[74:75], off
	v_lshl_add_u64 v[74:75], v[216:217], 0, s[74:75]
	s_add_i32 m0, s13, 0x2000
	s_nop 0
	global_load_lds_dwordx4 v[74:75], off
	s_mov_b32 m0, s19
	v_lshl_add_u64 v[74:75], v[218:219], 0, s[64:65]
	global_load_lds_dwordx4 v[218:219], off
	s_mov_b32 m0, s52
	s_nop 0
	global_load_lds_dwordx4 v[74:75], off
	s_waitcnt vmcnt(9)
	s_waitcnt lgkmcnt(0)
	s_setprio 1
	s_barrier
; #define PG8_STAGE(bufoff, gbase, voff) do { _Pragma("unroll") for (int _i = 0; _i < 2; ++_i) \
;         __builtin_amdgcn_global_load_lds((const unsigned*)((const char*)(gbase) + (size_t)_i * qstep + (voff)[0]), (PG8_LAS unsigned*)(lds + (bufoff) + ldsw + _i * 8192), 16, 0, 0); } while (0)
; #define PG8_LDA(dst, b, h) do { _Pragma("unroll") for (int m = 0; m < 4; ++m) _Pragma("unroll") for (int k = 0; k < 2; ++k) dst[m][k] = *(const PG8_LAS bf16x8*)(lds + PG8_SA(b, h) + aoff + m * 2048 + k * 1024); } while (0)
; #define PG8_LDB(dst, b, h) do { _Pragma("unroll") for (int n = 0; n < 2; ++n) _Pragma("unroll") for (int k = 0; k < 2; ++k) dst[n][k] = *(const PG8_LAS bf16x8*)(lds + PG8_SB(b, h) + boff + n * 2048 + k * 1024); } while (0)
; #define PG8_MMA(ai, bj, At, Bt) do { __builtin_amdgcn_s_setprio(1); _Pragma("unroll") for (int m = 0; m < 4; ++m) _Pragma("unroll") for (int n = 0; n < 2; ++n) _Pragma("unroll") for (int k = 0; k < 2; ++k) \
;         acc[ai][bj][m][n] = __builtin_amdgcn_mfma_f32_16x16x32_bf16(Bt[n][k], At[m][k], acc[ai][bj][m][n], 0, 0, 0); __builtin_amdgcn_s_setprio(0); } while (0)
; #define PG8_WAIT_V89() do { if constexpr (SLIVER) PG8_WAIT_V(9); else PG8_WAIT_V(8); } while (0)
; #define PG8_STAGE_S(b, gbase) do { if constexpr (SLIVER) __builtin_amdgcn_global_load_lds((const unsigned*)((const char*)(gbase) + voffS), (PG8_LAS unsigned*)(lds + STAGE_BYTES + (b) * 2048 + wid * 256), 4, 0, 0); } while (0)
; #define PG8_WAIT_L(n) asm volatile("s_waitcnt lgkmcnt(" #n ")" ::: "memory")
; #define PG8_BAR __builtin_amdgcn_s_barrier()
; #define PG8_SCHED __builtin_amdgcn_sched_barrier(0)
; template <class Epi, class Sched, bool ALIGN_EPI = false, bool SP2 = false, bool SLIVER = false>
; __device__ __forceinline__ void gemm_phase(PG8_LAS unsigned char* lds, const Gemm g, const Sched& S, const Epi& E) {
;     ...
;             PG8_WAIT_V89(); PG8_WAIT_L(0); PG8_BAR; PG8_MMA(1, 0, At, B0); PG8_MMA(1, 1, At, B1); PG8_MMA_S(); PG8_BAR; PG8_SCHED;
;             PG8_LDB(B0, 1, 0); PG8_LDB(B1, 1, 1); PG8_SCHED; PG8_LDA(At, 1, 0); PG8_STAGE(PG8_SA(0, 1), a2 + hstep, voffA); PG8_STAGE_S(0, s2);
;             PG8_WAIT_V89(); PG8_WAIT_L(0); PG8_BAR; PG8_MMA(0, 0, At, B0); PG8_MMA(0, 1, At, B1); PG8_BAR; PG8_SCHED;
	v_mfma_f32_16x16x32_bf16 v[74:77], v[154:157], v[66:69], v[86:89]
	v_mfma_f32_16x16x32_bf16 v[74:77], v[158:161], v[70:73], v[74:77]
	v_mfma_f32_16x16x32_bf16 v[78:81], v[162:165], v[66:69], v[82:85]
	v_mfma_f32_16x16x32_bf16 v[78:81], v[174:177], v[70:73], v[78:81]
	v_mfma_f32_16x16x32_bf16 v[54:57], v[154:157], v[224:227], v[54:57]
	v_mfma_f32_16x16x32_bf16 v[54:57], v[158:161], v[228:231], v[54:57]
	v_mfma_f32_16x16x32_bf16 v[50:53], v[162:165], v[224:227], v[50:53]
	v_mfma_f32_16x16x32_bf16 v[50:53], v[174:177], v[228:231], v[50:53]
	v_mfma_f32_16x16x32_bf16 v[38:41], v[154:157], v[232:235], v[38:41]
	v_mfma_f32_16x16x32_bf16 v[38:41], v[158:161], v[240:243], v[38:41]
	v_mfma_f32_16x16x32_bf16 v[34:37], v[162:165], v[232:235], v[34:37]
	v_mfma_f32_16x16x32_bf16 v[34:37], v[174:177], v[240:243], v[34:37]
	v_mfma_f32_16x16x32_bf16 v[22:25], v[154:157], v[244:247], v[22:25]
	v_mfma_f32_16x16x32_bf16 v[22:25], v[158:161], v[248:251], v[22:25]
	v_mfma_f32_16x16x32_bf16 v[18:21], v[162:165], v[244:247], v[18:21]
	v_mfma_f32_16x16x32_bf16 v[18:21], v[174:177], v[248:251], v[18:21]
	s_setprio 0
	s_setprio 1
	v_mfma_f32_16x16x32_bf16 v[10:13], v[180:183], v[248:251], v[10:13]
	v_mfma_f32_16x16x32_bf16 v[10:13], v[192:195], v[244:247], v[10:13]
	v_mfma_f32_16x16x32_bf16 v[58:61], v[192:195], v[66:69], v[58:61]
	v_mfma_f32_16x16x32_bf16 v[58:61], v[180:183], v[70:73], v[58:61]
	v_mfma_f32_16x16x32_bf16 v[62:65], v[188:191], v[70:73], v[62:65]
	v_mfma_f32_16x16x32_bf16 v[62:65], v[184:187], v[66:69], v[62:65]
	v_mfma_f32_16x16x32_bf16 v[46:49], v[184:187], v[224:227], v[46:49]
	v_mfma_f32_16x16x32_bf16 v[46:49], v[188:191], v[228:231], v[46:49]
	v_mfma_f32_16x16x32_bf16 v[42:45], v[180:183], v[228:231], v[42:45]
	v_mfma_f32_16x16x32_bf16 v[42:45], v[192:195], v[224:227], v[42:45]
	v_mfma_f32_16x16x32_bf16 v[26:29], v[192:195], v[232:235], v[26:29]
	v_mfma_f32_16x16x32_bf16 v[26:29], v[180:183], v[240:243], v[26:29]
	v_mfma_f32_16x16x32_bf16 v[30:33], v[188:191], v[240:243], v[30:33]
	v_mfma_f32_16x16x32_bf16 v[30:33], v[184:187], v[232:235], v[30:33]
	v_mfma_f32_16x16x32_bf16 v[14:17], v[184:187], v[244:247], v[14:17]
	v_mfma_f32_16x16x32_bf16 v[14:17], v[188:191], v[248:251], v[14:17]
	s_setprio 0
	s_setprio 1
	s_and_b64 vcc, exec, s[82:83]
	s_cbranch_vccz .Lslv_b2
	v_mfma_f32_16x16x32_bf16 v[66:69], v[184:187], v[166:169], v[6:9]
	v_mfma_f32_16x16x32_bf16 v[66:69], v[188:191], v[170:173], v[66:69]
	v_mfma_f32_16x16x32_bf16 v[70:73], v[180:183], v[170:173], v[2:5]
	v_mfma_f32_16x16x32_bf16 v[70:73], v[192:195], v[166:169], v[70:73]
	s_branch .LBB0_815
.LBB0_813:
.Lslv_b2:
	v_mfma_f32_16x16x32_bf16 v[6:9], v[154:157], v[166:169], v[6:9]
	v_mfma_f32_16x16x32_bf16 v[66:69], v[158:161], v[170:173], v[6:9]
	v_mfma_f32_16x16x32_bf16 v[2:5], v[174:177], v[170:173], v[2:5]
	v_mfma_f32_16x16x32_bf16 v[70:73], v[162:165], v[166:169], v[2:5]
.LBB0_815:
	s_barrier
	s_setprio 0
	s_add_u32 s13, s92, s62
	s_addc_u32 s66, s93, s63
	s_add_u32 s13, s13, 0x100
	s_addc_u32 s68, s66, 0
	s_and_b64 s[66:67], s[80:81], exec
	s_cselect_b32 s67, s89, s68
	s_cselect_b32 s66, s88, s13
	s_add_i32 s13, 0, 0x18000
	v_add_u32_e32 v2, s13, v220
	s_add_i32 s68, 0, 0x1c000
	ds_read_b128 v[154:157], v2
	ds_read_b128 v[158:161], v2 offset:1024
	ds_read_b128 v[162:165], v2 offset:2048
	ds_read_b128 v[174:177], v2 offset:3072
	v_add_u32_e32 v2, s68, v220
	ds_read_b128 v[184:187], v2
	ds_read_b128 v[188:191], v2 offset:1024
	ds_read_b128 v[192:195], v2 offset:2048
	ds_read_b128 v[180:183], v2 offset:3072
	s_mov_b32 m0, s53
	v_lshl_add_u64 v[166:167], v[218:219], 0, s[0:1]
	ds_read_b128 v[2:5], v223 offset:32768
	ds_read_b128 v[6:9], v223 offset:33792
	ds_read_b128 v[82:85], v223 offset:34816
	ds_read_b128 v[86:89], v223 offset:35840
	ds_read_b128 v[224:227], v223 offset:36864
	ds_read_b128 v[228:231], v223 offset:37888
	ds_read_b128 v[232:235], v223 offset:38912
	ds_read_b128 v[240:243], v223 offset:39936
	global_load_lds_dwordx4 v[166:167], off
	v_lshl_add_u64 v[166:167], v[218:219], 0, s[74:75]
	s_mov_b32 m0, s54
	s_nop 0
	global_load_lds_dwordx4 v[166:167], off
	v_lshl_add_u64 v[166:167], s[66:67], 0, v[200:201]
	s_mov_b32 m0, s55
	s_nop 0
	global_load_lds_dword v[166:167], off
	s_waitcnt vmcnt(9)
	s_waitcnt lgkmcnt(0)
	s_setprio 1
	s_barrier
; #define PG8_SB(B) __builtin_amdgcn_rcpf(1.f + expneg(B))
; #define PG8_SB(B) __builtin_amdgcn_rcpf(1.f + expneg(B))
; #define PG8_STAGE(bufoff, gbase, voff) do { _Pragma("unroll") for (int _i = 0; _i < 2; ++_i) \
;         __builtin_amdgcn_global_load_lds((const unsigned*)((const char*)(gbase) + (size_t)_i * qstep + (voff)[0]), (PG8_LAS unsigned*)(lds + (bufoff) + ldsw + _i * 8192), 16, 0, 0); } while (0)
; #define PG8_LDA(dst, b, h) do { _Pragma("unroll") for (int m = 0; m < 4; ++m) _Pragma("unroll") for (int k = 0; k < 2; ++k) dst[m][k] = *(const PG8_LAS bf16x8*)(lds + PG8_SA(b, h) + aoff + m * 2048 + k * 1024); } while (0)
; #define PG8_MMA(ai, bj, At, Bt) do { __builtin_amdgcn_s_setprio(1); _Pragma("unroll") for (int m = 0; m < 4; ++m) _Pragma("unroll") for (int n = 0; n < 2; ++n) _Pragma("unroll") for (int k = 0; k < 2; ++k) \
;         acc[ai][bj][m][n] = __builtin_amdgcn_mfma_f32_16x16x32_bf16(Bt[n][k], At[m][k], acc[ai][bj][m][n], 0, 0, 0); __builtin_amdgcn_s_setprio(0); } while (0)
; #define PG8_WAIT_V89() do { if constexpr (SLIVER) PG8_WAIT_V(9); else PG8_WAIT_V(8); } while (0)
; #define PG8_LDS_S(b) do { if constexpr (SLIVER) { Sf[0] = *(const PG8_LAS bf16x8*)(lds + STAGE_BYTES + (b) * 2048 + soff0); Sf[1] = *(const PG8_LAS bf16x8*)(lds + STAGE_BYTES + (b) * 2048 + (soff0 ^ 64)); } } while (0)
; #define PG8_WAIT_L(n) asm volatile("s_waitcnt lgkmcnt(" #n ")" ::: "memory")
; #define PG8_BAR __builtin_amdgcn_s_barrier()
; #define PG8_SCHED __builtin_amdgcn_sched_barrier(0)
; template <class Epi, class Sched, bool ALIGN_EPI = false, bool SP2 = false, bool SLIVER = false>
; __device__ __forceinline__ void gemm_phase(PG8_LAS unsigned char* lds, const Gemm g, const Sched& S, const Epi& E) {
;     ...
;             PG8_WAIT_V89(); PG8_WAIT_L(0); PG8_BAR; PG8_MMA(0, 0, At, B0); PG8_MMA(0, 1, At, B1); PG8_BAR; PG8_SCHED;
;             PG8_LDA(At, 1, 1); PG8_LDS_S(1); PG8_STAGE(PG8_SB(1, 0), b3, voffB); PG8_STAGE(PG8_SB(1, 1), b3 + hstep, voffB); PG8_STAGE(PG8_SA(1, 0), a3, voffA);
;             PG8_WAIT_V89(); PG8_WAIT_L(0); PG8_BAR; PG8_MMA(1, 0, At, B0); PG8_MMA(1, 1, At, B1); PG8_MMA_S(); PG8_BAR; PG8_SCHED;
	v_mfma_f32_16x16x32_bf16 v[146:149], v[154:157], v[2:5], v[146:149]
	v_mfma_f32_16x16x32_bf16 v[170:173], v[158:161], v[6:9], v[146:149]
	v_mfma_f32_16x16x32_bf16 v[146:149], v[162:165], v[2:5], v[150:153]
	v_mfma_f32_16x16x32_bf16 v[166:169], v[174:177], v[6:9], v[146:149]
	v_mfma_f32_16x16x32_bf16 v[134:137], v[154:157], v[82:85], v[134:137]
	v_mfma_f32_16x16x32_bf16 v[134:137], v[158:161], v[86:89], v[134:137]
	v_mfma_f32_16x16x32_bf16 v[130:133], v[162:165], v[82:85], v[130:133]
	v_mfma_f32_16x16x32_bf16 v[130:133], v[174:177], v[86:89], v[130:133]
	v_mfma_f32_16x16x32_bf16 v[118:121], v[154:157], v[224:227], v[118:121]
	v_mfma_f32_16x16x32_bf16 v[118:121], v[158:161], v[228:231], v[118:121]
	v_mfma_f32_16x16x32_bf16 v[114:117], v[162:165], v[224:227], v[114:117]
	v_mfma_f32_16x16x32_bf16 v[114:117], v[174:177], v[228:231], v[114:117]
	v_mfma_f32_16x16x32_bf16 v[102:105], v[154:157], v[232:235], v[102:105]
	v_mfma_f32_16x16x32_bf16 v[102:105], v[158:161], v[240:243], v[102:105]
	v_mfma_f32_16x16x32_bf16 v[98:101], v[162:165], v[232:235], v[98:101]
	v_mfma_f32_16x16x32_bf16 v[98:101], v[174:177], v[240:243], v[98:101]
	s_setprio 0
	s_setprio 1
	v_mfma_f32_16x16x32_bf16 v[142:145], v[184:187], v[2:5], v[142:145]
	v_mfma_f32_16x16x32_bf16 v[142:145], v[188:191], v[6:9], v[142:145]
	v_mfma_f32_16x16x32_bf16 v[2:5], v[192:195], v[2:5], v[138:141]
	v_mfma_f32_16x16x32_bf16 v[138:141], v[180:183], v[6:9], v[2:5]
	v_mfma_f32_16x16x32_bf16 v[2:5], v[184:187], v[82:85], v[126:129]
	v_mfma_f32_16x16x32_bf16 v[126:129], v[188:191], v[86:89], v[2:5]
	v_mfma_f32_16x16x32_bf16 v[2:5], v[192:195], v[82:85], v[122:125]
	v_mfma_f32_16x16x32_bf16 v[122:125], v[180:183], v[86:89], v[2:5]
	v_mfma_f32_16x16x32_bf16 v[2:5], v[184:187], v[224:227], v[110:113]
	v_mfma_f32_16x16x32_bf16 v[110:113], v[188:191], v[228:231], v[2:5]
	v_mfma_f32_16x16x32_bf16 v[2:5], v[192:195], v[224:227], v[106:109]
	v_mfma_f32_16x16x32_bf16 v[106:109], v[180:183], v[228:231], v[2:5]
	v_mfma_f32_16x16x32_bf16 v[2:5], v[184:187], v[232:235], v[94:97]
	v_mfma_f32_16x16x32_bf16 v[94:97], v[188:191], v[240:243], v[2:5]
	v_mfma_f32_16x16x32_bf16 v[2:5], v[192:195], v[232:235], v[90:93]
	v_mfma_f32_16x16x32_bf16 v[90:93], v[180:183], v[240:243], v[2:5]
	s_barrier
	s_setprio 0
	s_add_i32 s66, 0, 0x20800
	v_add_u32_e32 v82, s66, v221
	v_add_u32_e32 v83, s66, v222
	s_add_i32 s13, s13, s18
	ds_read_b128 v[2:5], v223 offset:49152
	ds_read_b128 v[6:9], v223 offset:50176
	ds_read_b128 v[224:227], v223 offset:51200
	ds_read_b128 v[228:231], v223 offset:52224
	ds_read_b128 v[232:235], v223 offset:53248
	ds_read_b128 v[240:243], v223 offset:54272
	ds_read_b128 v[244:247], v223 offset:55296
	ds_read_b128 v[248:251], v223 offset:56320
	ds_read_b128 v[146:149], v82
	ds_read_b128 v[150:153], v83
	v_lshl_add_u64 v[82:83], v[216:217], 0, s[26:27]
	s_mov_b32 m0, s13
	s_mov_b64 s[66:67], 0x210080
	global_load_lds_dwordx4 v[82:83], off
	v_lshl_add_u64 v[82:83], v[216:217], 0, s[60:61]
	s_add_i32 m0, s13, 0x2000
	s_add_i32 s13, s68, s18
	global_load_lds_dwordx4 v[82:83], off
	v_lshl_add_u64 v[82:83], v[216:217], 0, s[8:9]
	s_mov_b32 m0, s13
	s_nop 0
	global_load_lds_dwordx4 v[82:83], off
	v_lshl_add_u64 v[82:83], v[216:217], 0, s[66:67]
	s_add_i32 m0, s13, 0x2000
	s_nop 0
	global_load_lds_dwordx4 v[82:83], off
	v_lshl_add_u64 v[82:83], v[218:219], 0, s[26:27]
	s_mov_b32 m0, s10
	s_nop 0
	global_load_lds_dwordx4 v[82:83], off
	v_lshl_add_u64 v[82:83], v[218:219], 0, s[60:61]
	s_mov_b32 m0, s48
	s_nop 0
	global_load_lds_dwordx4 v[82:83], off
	s_waitcnt vmcnt(9)
	s_waitcnt lgkmcnt(0)
	s_setprio 1
	s_barrier
	v_mfma_f32_16x16x32_bf16 v[74:77], v[154:157], v[2:5], v[74:77]
	v_mfma_f32_16x16x32_bf16 v[86:89], v[158:161], v[6:9], v[74:77]
	v_mfma_f32_16x16x32_bf16 v[74:77], v[162:165], v[2:5], v[78:81]
	v_mfma_f32_16x16x32_bf16 v[82:85], v[174:177], v[6:9], v[74:77]
	v_mfma_f32_16x16x32_bf16 v[54:57], v[154:157], v[224:227], v[54:57]
	v_mfma_f32_16x16x32_bf16 v[54:57], v[158:161], v[228:231], v[54:57]
	v_mfma_f32_16x16x32_bf16 v[50:53], v[162:165], v[224:227], v[50:53]
	v_mfma_f32_16x16x32_bf16 v[50:53], v[174:177], v[228:231], v[50:53]
	v_mfma_f32_16x16x32_bf16 v[38:41], v[154:157], v[232:235], v[38:41]
	v_mfma_f32_16x16x32_bf16 v[38:41], v[158:161], v[240:243], v[38:41]
	v_mfma_f32_16x16x32_bf16 v[34:37], v[162:165], v[232:235], v[34:37]
	v_mfma_f32_16x16x32_bf16 v[34:37], v[174:177], v[240:243], v[34:37]
	v_mfma_f32_16x16x32_bf16 v[22:25], v[154:157], v[244:247], v[22:25]
	v_mfma_f32_16x16x32_bf16 v[22:25], v[158:161], v[248:251], v[22:25]
	v_mfma_f32_16x16x32_bf16 v[18:21], v[162:165], v[244:247], v[18:21]
	v_mfma_f32_16x16x32_bf16 v[18:21], v[174:177], v[248:251], v[18:21]
	s_setprio 0
	s_setprio 1
	v_mfma_f32_16x16x32_bf16 v[62:65], v[184:187], v[2:5], v[62:65]
	v_mfma_f32_16x16x32_bf16 v[62:65], v[188:191], v[6:9], v[62:65]
	v_mfma_f32_16x16x32_bf16 v[2:5], v[192:195], v[2:5], v[58:61]
	v_mfma_f32_16x16x32_bf16 v[58:61], v[180:183], v[6:9], v[2:5]
	v_mfma_f32_16x16x32_bf16 v[2:5], v[184:187], v[224:227], v[46:49]
	v_mfma_f32_16x16x32_bf16 v[46:49], v[188:191], v[228:231], v[2:5]
	v_mfma_f32_16x16x32_bf16 v[2:5], v[192:195], v[224:227], v[42:45]
	v_mfma_f32_16x16x32_bf16 v[42:45], v[180:183], v[228:231], v[2:5]
	v_mfma_f32_16x16x32_bf16 v[2:5], v[184:187], v[232:235], v[30:33]
	v_mfma_f32_16x16x32_bf16 v[30:33], v[188:191], v[240:243], v[2:5]
	v_mfma_f32_16x16x32_bf16 v[2:5], v[192:195], v[232:235], v[26:29]
	v_mfma_f32_16x16x32_bf16 v[26:29], v[180:183], v[240:243], v[2:5]
	v_mfma_f32_16x16x32_bf16 v[2:5], v[184:187], v[244:247], v[14:17]
	v_mfma_f32_16x16x32_bf16 v[14:17], v[188:191], v[248:251], v[2:5]
	v_mfma_f32_16x16x32_bf16 v[2:5], v[192:195], v[244:247], v[10:13]
	v_mfma_f32_16x16x32_bf16 v[10:13], v[180:183], v[248:251], v[2:5]
	s_setprio 0
	s_setprio 1
	s_and_b64 vcc, exec, s[82:83]
	s_cbranch_vccz .Lslv_c2
	v_mfma_f32_16x16x32_bf16 v[2:5], v[184:187], v[146:149], v[66:69]
	v_mfma_f32_16x16x32_bf16 v[6:9], v[188:191], v[150:153], v[2:5]
	v_mfma_f32_16x16x32_bf16 v[2:5], v[180:183], v[150:153], v[70:73]
	v_mfma_f32_16x16x32_bf16 v[2:5], v[192:195], v[146:149], v[2:5]
	s_branch .LBB0_810
.LBB0_817:
.Lslv_c2:
	v_mfma_f32_16x16x32_bf16 v[2:5], v[154:157], v[146:149], v[66:69]
	v_mfma_f32_16x16x32_bf16 v[6:9], v[158:161], v[150:153], v[2:5]
	v_mfma_f32_16x16x32_bf16 v[2:5], v[174:177], v[150:153], v[70:73]
	v_mfma_f32_16x16x32_bf16 v[2:5], v[162:165], v[146:149], v[2:5]
	s_branch .LBB0_810

; #define PG8_STAGE(bufoff, gbase, voff) do { _Pragma("unroll") for (int _i = 0; _i < 2; ++_i) \
;         __builtin_amdgcn_global_load_lds((const unsigned*)((const char*)(gbase) + (size_t)_i * qstep + (voff)[0]), (PG8_LAS unsigned*)(lds + (bufoff) + ldsw + _i * 8192), 16, 0, 0); } while (0)
; #define PG8_LDA(dst, b, h) do { _Pragma("unroll") for (int m = 0; m < 4; ++m) _Pragma("unroll") for (int k = 0; k < 2; ++k) dst[m][k] = *(const PG8_LAS bf16x8*)(lds + PG8_SA(b, h) + aoff + m * 2048 + k * 1024); } while (0)
; #define PG8_LDB(dst, b, h) do { _Pragma("unroll") for (int n = 0; n < 2; ++n) _Pragma("unroll") for (int k = 0; k < 2; ++k) dst[n][k] = *(const PG8_LAS bf16x8*)(lds + PG8_SB(b, h) + boff + n * 2048 + k * 1024); } while (0)
; #define PG8_WAIT_V89() do { if constexpr (SLIVER) PG8_WAIT_V(9); else PG8_WAIT_V(8); } while (0)
; #define PG8_WAIT_L(n) asm volatile("s_waitcnt lgkmcnt(" #n ")" ::: "memory")
; template <class Epi, class Sched, bool ALIGN_EPI = false, bool SP2 = false, bool SLIVER = false>
; __device__ __forceinline__ void gemm_phase(PG8_LAS unsigned char* lds, const Gemm g, const Sched& S, const Epi& E) {
;     ...
;         const bool has_next = S.next(ui + 1, nxt);
;         const char* nA = has_next ? (const char*)g.A + (size_t)nxt.pm * tstep + Epi::k0(nxt.seg) * 2 : cA; const char* nB = has_next ? (const char*)g.Bt + (size_t)nxt.pn * tstep + Epi::k0(nxt.seg) * 2 : cB;
;         const char* nS = has_next ? (const char*)g.A + (size_t)S.srow0 * K * 2 + (size_t)nxt.pm * sstep + Epi::k0(nxt.seg) * 2 : cS;
;         for (int t = 0; t < nt; t += 2) {
;             const bool last = (t == nt - 2);
;             const char* a1 = cA + (size_t)(t + 1) * kstep;
;             const char* a2 = last ? nA : cA + (size_t)(t + 2) * kstep; const char* b2 = last ? nB : cB + (size_t)(t + 2) * kstep;
;             const char* a3 = a2 + kstep; const char* b3 = b2 + kstep;
;             const char* s1 = cS + (size_t)(t + 1) * kstep; const char* s2 = last ? nS : cS + (size_t)(t + 2) * kstep;
;             if (last && has_next) S.a_ready(nxt);
;             if constexpr (SP2) {
;             PG8_LDB(B0, 0, 0); PG8_LDB(B1, 0, 1); PG8_SCHED; PG8_LDA(At, 0, 0); PG8_STAGE(PG8_SA(1, 1), a1 + hstep, voffA); PG8_STAGE_S(1, s1);
;             PG8_WAIT_V89(); PG8_WAIT_L(0); PG8_BAR; PG8_MMA(0, 0, At, B0); PG8_MMA(0, 1, At, B1); PG8_BAR; PG8_SCHED;
.LBB0_934:
	s_cmp_eq_u32 s66, s62
	s_cselect_b64 s[80:81], -1, 0
	s_add_u32 s12, s42, s62
	s_addc_u32 s13, s43, s63
	s_add_u32 s40, s12, 0x100
	s_addc_u32 s41, s13, 0
	s_and_b64 s[12:13], s[80:81], exec
	s_cselect_b32 s41, s95, s41
	s_cselect_b32 s40, s94, s40
	s_add_u32 s68, s17, s62
	s_addc_u32 s69, s45, s63
	s_add_i32 s76, 0, 0x10000
	s_and_b64 s[12:13], s[80:81], exec
	v_add_u32_e32 v138, s76, v212
	s_cselect_b32 s13, s97, s69
	s_cselect_b32 s12, s96, s68
	s_add_i32 s68, 0, 0x14000
	ds_read_b128 v[146:149], v138
	ds_read_b128 v[150:153], v138 offset:1024
	ds_read_b128 v[154:157], v138 offset:2048
	ds_read_b128 v[158:161], v138 offset:3072
	v_add_u32_e32 v138, s68, v212
	ds_read_b128 v[166:169], v138
	ds_read_b128 v[170:173], v138 offset:1024
	ds_read_b128 v[174:177], v138 offset:2048
	ds_read_b128 v[162:165], v138 offset:3072
	v_lshl_add_u64 v[202:203], v[198:199], 0, s[62:63]
	s_mov_b64 vcc, 0x90080
	v_lshl_add_u64 v[208:209], v[202:203], 0, vcc
	s_add_i32 m0, s93, 0xc000
	s_mov_b64 vcc, 0xd8080
	ds_read_b128 v[138:141], v215
	ds_read_b128 v[142:145], v215 offset:1024
	ds_read_b128 v[180:183], v215 offset:2048
	ds_read_b128 v[184:187], v215 offset:3072
	ds_read_b128 v[216:219], v215 offset:4096
	ds_read_b128 v[220:223], v215 offset:5120
	ds_read_b128 v[224:227], v215 offset:6144
	ds_read_b128 v[228:231], v215 offset:7168
	global_load_lds_dwordx4 v[208:209], off
	v_lshl_add_u64 v[202:203], v[202:203], 0, vcc
	s_add_i32 m0, s93, 0xe000
	s_nop 0
	global_load_lds_dwordx4 v[202:203], off
	v_lshl_add_u64 v[202:203], v[200:201], 0, s[62:63]
	s_add_i32 m0, s50, 0x20800
	s_nop 0
	global_load_lds_dword v[202:203], off
	s_waitcnt vmcnt(9)
	s_waitcnt lgkmcnt(0)
	s_setprio 1
	s_barrier
	v_mfma_f32_16x16x32_bf16 v[134:137], v[146:149], v[138:141], v[134:137]
	v_mfma_f32_16x16x32_bf16 v[134:137], v[150:153], v[142:145], v[134:137]
	v_mfma_f32_16x16x32_bf16 v[130:133], v[158:161], v[142:145], v[130:133]
	v_mfma_f32_16x16x32_bf16 v[130:133], v[154:157], v[138:141], v[130:133]
	v_mfma_f32_16x16x32_bf16 v[122:125], v[154:157], v[180:183], v[122:125]
	v_mfma_f32_16x16x32_bf16 v[122:125], v[158:161], v[184:187], v[122:125]
	v_mfma_f32_16x16x32_bf16 v[126:129], v[150:153], v[184:187], v[126:129]
	v_mfma_f32_16x16x32_bf16 v[126:129], v[146:149], v[180:183], v[126:129]
	v_mfma_f32_16x16x32_bf16 v[114:117], v[146:149], v[216:219], v[114:117]
	v_mfma_f32_16x16x32_bf16 v[114:117], v[150:153], v[220:223], v[114:117]
	v_mfma_f32_16x16x32_bf16 v[106:109], v[158:161], v[220:223], v[106:109]
	v_mfma_f32_16x16x32_bf16 v[106:109], v[154:157], v[216:219], v[106:109]
	v_mfma_f32_16x16x32_bf16 v[90:93], v[154:157], v[224:227], v[90:93]
	v_mfma_f32_16x16x32_bf16 v[90:93], v[158:161], v[228:231], v[90:93]
	v_mfma_f32_16x16x32_bf16 v[98:101], v[150:153], v[228:231], v[98:101]
	v_mfma_f32_16x16x32_bf16 v[98:101], v[146:149], v[224:227], v[98:101]
	s_setprio 0
	s_setprio 1
	v_mfma_f32_16x16x32_bf16 v[74:77], v[174:177], v[224:227], v[74:77]
	v_mfma_f32_16x16x32_bf16 v[74:77], v[162:165], v[228:231], v[74:77]
	v_mfma_f32_16x16x32_bf16 v[110:113], v[162:165], v[142:145], v[110:113]
	v_mfma_f32_16x16x32_bf16 v[110:113], v[174:177], v[138:141], v[110:113]
	v_mfma_f32_16x16x32_bf16 v[118:121], v[166:169], v[138:141], v[118:121]
	v_mfma_f32_16x16x32_bf16 v[118:121], v[170:173], v[142:145], v[118:121]
	v_mfma_f32_16x16x32_bf16 v[102:105], v[170:173], v[184:187], v[102:105]
	v_mfma_f32_16x16x32_bf16 v[102:105], v[166:169], v[180:183], v[102:105]
	v_mfma_f32_16x16x32_bf16 v[94:97], v[174:177], v[180:183], v[94:97]
	v_mfma_f32_16x16x32_bf16 v[94:97], v[162:165], v[184:187], v[94:97]
	v_mfma_f32_16x16x32_bf16 v[82:85], v[162:165], v[220:223], v[82:85]
	v_mfma_f32_16x16x32_bf16 v[82:85], v[174:177], v[216:219], v[82:85]
	v_mfma_f32_16x16x32_bf16 v[86:89], v[166:169], v[216:219], v[86:89]
	v_mfma_f32_16x16x32_bf16 v[86:89], v[170:173], v[220:223], v[86:89]
	v_mfma_f32_16x16x32_bf16 v[78:81], v[170:173], v[228:231], v[78:81]
	v_mfma_f32_16x16x32_bf16 v[78:81], v[166:169], v[224:227], v[78:81]
	s_barrier
; #define PG8_SB(B) __builtin_amdgcn_rcpf(1.f + expneg(B))
; #define PG8_SB(B) __builtin_amdgcn_rcpf(1.f + expneg(B))
; #define PG8_STAGE(bufoff, gbase, voff) do { _Pragma("unroll") for (int _i = 0; _i < 2; ++_i) \
;         __builtin_amdgcn_global_load_lds((const unsigned*)((const char*)(gbase) + (size_t)_i * qstep + (voff)[0]), (PG8_LAS unsigned*)(lds + (bufoff) + ldsw + _i * 8192), 16, 0, 0); } while (0)
; #define PG8_LDA(dst, b, h) do { _Pragma("unroll") for (int m = 0; m < 4; ++m) _Pragma("unroll") for (int k = 0; k < 2; ++k) dst[m][k] = *(const PG8_LAS bf16x8*)(lds + PG8_SA(b, h) + aoff + m * 2048 + k * 1024); } while (0)
; #define PG8_MMA(ai, bj, At, Bt) do { __builtin_amdgcn_s_setprio(1); _Pragma("unroll") for (int m = 0; m < 4; ++m) _Pragma("unroll") for (int n = 0; n < 2; ++n) _Pragma("unroll") for (int k = 0; k < 2; ++k) \
;         acc[ai][bj][m][n] = __builtin_amdgcn_mfma_f32_16x16x32_bf16(Bt[n][k], At[m][k], acc[ai][bj][m][n], 0, 0, 0); __builtin_amdgcn_s_setprio(0); } while (0)
; #define PG8_WAIT_V89() do { if constexpr (SLIVER) PG8_WAIT_V(9); else PG8_WAIT_V(8); } while (0)
; #define PG8_LDS_S(b) do { if constexpr (SLIVER) { Sf[0] = *(const PG8_LAS bf16x8*)(lds + STAGE_BYTES + (b) * 2048 + soff0); Sf[1] = *(const PG8_LAS bf16x8*)(lds + STAGE_BYTES + (b) * 2048 + (soff0 ^ 64)); } } while (0)
; #define PG8_WAIT_L(n) asm volatile("s_waitcnt lgkmcnt(" #n ")" ::: "memory")
; #define PG8_BAR __builtin_amdgcn_s_barrier()
; #define PG8_SCHED __builtin_amdgcn_sched_barrier(0)
; template <class Epi, class Sched, bool ALIGN_EPI = false, bool SP2 = false, bool SLIVER = false>
; __device__ __forceinline__ void gemm_phase(PG8_LAS unsigned char* lds, const Gemm g, const Sched& S, const Epi& E) {
;     ...
;             PG8_LDA(At, 0, 1); PG8_LDS_S(0); PG8_STAGE(PG8_SB(0, 0), b2, voffB); PG8_STAGE(PG8_SB(0, 1), b2 + hstep, voffB); PG8_STAGE(PG8_SA(0, 0), a2, voffA);
;             PG8_WAIT_V89(); PG8_WAIT_L(0); PG8_BAR; PG8_MMA(1, 0, At, B0); PG8_MMA(1, 1, At, B1); PG8_MMA_S(); PG8_BAR; PG8_SCHED;
	s_setprio 0
	s_add_i32 s69, 0, 0x20000
	v_lshl_add_u64 v[202:203], s[12:13], 0, v[190:191]
	s_add_i32 s12, s76, s92
	v_add_u32_e32 v178, s69, v213
	v_add_u32_e32 v184, s69, v214
	s_mov_b32 m0, s12
	ds_read_b128 v[138:141], v215 offset:16384
	ds_read_b128 v[142:145], v215 offset:17408
	ds_read_b128 v[216:219], v215 offset:18432
	ds_read_b128 v[220:223], v215 offset:19456
	ds_read_b128 v[224:227], v215 offset:20480
	ds_read_b128 v[228:231], v215 offset:21504
	ds_read_b128 v[232:235], v215 offset:22528
	ds_read_b128 v[240:243], v215 offset:23552
	ds_read_b128 v[180:183], v178
	ds_read_b128 v[184:187], v184
	global_load_lds_dwordx4 v[202:203], off
	v_lshl_add_u64 v[208:209], v[202:203], 0, s[70:71]
	s_add_i32 m0, s12, 0x2000
	s_add_i32 s12, s68, s92
	global_load_lds_dwordx4 v[208:209], off
	v_lshl_add_u64 v[208:209], v[202:203], 0, s[46:47]
	s_mov_b32 m0, s12
	v_lshl_add_u64 v[210:211], s[40:41], 0, v[188:189]
	global_load_lds_dwordx4 v[208:209], off
	v_lshl_add_u64 v[208:209], v[202:203], 0, s[6:7]
	s_add_i32 m0, s12, 0x2000
	s_nop 0
	global_load_lds_dwordx4 v[208:209], off
	s_mov_b32 m0, s93
	v_lshl_add_u64 v[208:209], v[210:211], 0, s[70:71]
	global_load_lds_dwordx4 v[210:211], off
	s_mov_b32 m0, s48
	s_nop 0
	global_load_lds_dwordx4 v[208:209], off
	s_waitcnt vmcnt(9)
	s_waitcnt lgkmcnt(0)
	s_setprio 1
	s_barrier
	v_mfma_f32_16x16x32_bf16 v[70:73], v[146:149], v[138:141], v[70:73]
	v_mfma_f32_16x16x32_bf16 v[70:73], v[150:153], v[142:145], v[70:73]
	v_mfma_f32_16x16x32_bf16 v[66:69], v[158:161], v[142:145], v[66:69]
	v_mfma_f32_16x16x32_bf16 v[66:69], v[154:157], v[138:141], v[66:69]
	v_mfma_f32_16x16x32_bf16 v[58:61], v[154:157], v[216:219], v[58:61]
	v_mfma_f32_16x16x32_bf16 v[58:61], v[158:161], v[220:223], v[58:61]
	v_mfma_f32_16x16x32_bf16 v[62:65], v[150:153], v[220:223], v[62:65]
	v_mfma_f32_16x16x32_bf16 v[62:65], v[146:149], v[216:219], v[62:65]
	v_mfma_f32_16x16x32_bf16 v[50:53], v[146:149], v[224:227], v[50:53]
	v_mfma_f32_16x16x32_bf16 v[50:53], v[150:153], v[228:231], v[50:53]
	v_mfma_f32_16x16x32_bf16 v[42:45], v[158:161], v[228:231], v[42:45]
	v_mfma_f32_16x16x32_bf16 v[42:45], v[154:157], v[224:227], v[42:45]
	v_mfma_f32_16x16x32_bf16 v[26:29], v[154:157], v[232:235], v[26:29]
	v_mfma_f32_16x16x32_bf16 v[26:29], v[158:161], v[240:243], v[26:29]
	v_mfma_f32_16x16x32_bf16 v[34:37], v[150:153], v[240:243], v[34:37]
	v_mfma_f32_16x16x32_bf16 v[34:37], v[146:149], v[232:235], v[34:37]
	s_setprio 0
	s_setprio 1
	v_mfma_f32_16x16x32_bf16 v[10:13], v[174:177], v[232:235], v[10:13]
	v_mfma_f32_16x16x32_bf16 v[10:13], v[162:165], v[240:243], v[10:13]
	v_mfma_f32_16x16x32_bf16 v[46:49], v[162:165], v[142:145], v[46:49]
	v_mfma_f32_16x16x32_bf16 v[46:49], v[174:177], v[138:141], v[46:49]
	v_mfma_f32_16x16x32_bf16 v[54:57], v[166:169], v[138:141], v[54:57]
	v_mfma_f32_16x16x32_bf16 v[54:57], v[170:173], v[142:145], v[54:57]
	v_mfma_f32_16x16x32_bf16 v[38:41], v[170:173], v[220:223], v[38:41]
	v_mfma_f32_16x16x32_bf16 v[38:41], v[166:169], v[216:219], v[38:41]
	v_mfma_f32_16x16x32_bf16 v[30:33], v[174:177], v[216:219], v[30:33]
	v_mfma_f32_16x16x32_bf16 v[30:33], v[162:165], v[220:223], v[30:33]
	v_mfma_f32_16x16x32_bf16 v[18:21], v[162:165], v[228:231], v[18:21]
	v_mfma_f32_16x16x32_bf16 v[18:21], v[174:177], v[224:227], v[18:21]
	v_mfma_f32_16x16x32_bf16 v[22:25], v[166:169], v[224:227], v[22:25]
	v_mfma_f32_16x16x32_bf16 v[22:25], v[170:173], v[228:231], v[22:25]
	v_mfma_f32_16x16x32_bf16 v[14:17], v[170:173], v[240:243], v[14:17]
	v_mfma_f32_16x16x32_bf16 v[14:17], v[166:169], v[232:235], v[14:17]
	s_setprio 0
	s_setprio 1
	s_and_b64 vcc, exec, s[90:91]
	s_cbranch_vccz .Lslv_b3
	v_mfma_f32_16x16x32_bf16 v[138:141], v[166:169], v[180:183], v[6:9]
	v_mfma_f32_16x16x32_bf16 v[138:141], v[170:173], v[184:187], v[138:141]
	v_mfma_f32_16x16x32_bf16 v[142:145], v[162:165], v[184:187], v[2:5]
	v_mfma_f32_16x16x32_bf16 v[142:145], v[174:177], v[180:183], v[142:145]
	s_branch .LBB0_938

; #define PG8_STAGE(bufoff, gbase, voff) do { _Pragma("unroll") for (int _i = 0; _i < 2; ++_i) \
;         __builtin_amdgcn_global_load_lds((const unsigned*)((const char*)(gbase) + (size_t)_i * qstep + (voff)[0]), (PG8_LAS unsigned*)(lds + (bufoff) + ldsw + _i * 8192), 16, 0, 0); } while (0)
; #define PG8_LDA(dst, b, h) do { _Pragma("unroll") for (int m = 0; m < 4; ++m) _Pragma("unroll") for (int k = 0; k < 2; ++k) dst[m][k] = *(const PG8_LAS bf16x8*)(lds + PG8_SA(b, h) + aoff + m * 2048 + k * 1024); } while (0)
; #define PG8_LDB(dst, b, h) do { _Pragma("unroll") for (int n = 0; n < 2; ++n) _Pragma("unroll") for (int k = 0; k < 2; ++k) dst[n][k] = *(const PG8_LAS bf16x8*)(lds + PG8_SB(b, h) + boff + n * 2048 + k * 1024); } while (0)
; #define PG8_MMA(ai, bj, At, Bt) do { __builtin_amdgcn_s_setprio(1); _Pragma("unroll") for (int m = 0; m < 4; ++m) _Pragma("unroll") for (int n = 0; n < 2; ++n) _Pragma("unroll") for (int k = 0; k < 2; ++k) \
;         acc[ai][bj][m][n] = __builtin_amdgcn_mfma_f32_16x16x32_bf16(Bt[n][k], At[m][k], acc[ai][bj][m][n], 0, 0, 0); __builtin_amdgcn_s_setprio(0); } while (0)
; #define PG8_WAIT_V89() do { if constexpr (SLIVER) PG8_WAIT_V(9); else PG8_WAIT_V(8); } while (0)
; #define PG8_STAGE_S(b, gbase) do { if constexpr (SLIVER) __builtin_amdgcn_global_load_lds((const unsigned*)((const char*)(gbase) + voffS), (PG8_LAS unsigned*)(lds + STAGE_BYTES + (b) * 2048 + wid * 256), 4, 0, 0); } while (0)
; #define PG8_WAIT_L(n) asm volatile("s_waitcnt lgkmcnt(" #n ")" ::: "memory")
; #define PG8_BAR __builtin_amdgcn_s_barrier()
; #define PG8_SCHED __builtin_amdgcn_sched_barrier(0)
; template <class Epi, class Sched, bool ALIGN_EPI = false, bool SP2 = false, bool SLIVER = false>
; __device__ __forceinline__ void gemm_phase(PG8_LAS unsigned char* lds, const Gemm g, const Sched& S, const Epi& E) {
;     ...
;             PG8_LDB(B0, 1, 0); PG8_LDB(B1, 1, 1); PG8_SCHED; PG8_LDA(At, 1, 0); PG8_STAGE(PG8_SA(0, 1), a2 + hstep, voffA); PG8_STAGE_S(0, s2);
;             PG8_WAIT_V89(); PG8_WAIT_L(0); PG8_BAR; PG8_MMA(0, 0, At, B0); PG8_MMA(0, 1, At, B1); PG8_BAR; PG8_SCHED;
.LBB0_938:
	s_barrier
	s_setprio 0
	s_add_u32 s12, s54, s62
	s_addc_u32 s13, s55, s63
	s_add_u32 s68, s12, 0x100
	s_addc_u32 s69, s13, 0
	s_and_b64 s[12:13], s[80:81], exec
	s_cselect_b32 s13, s19, s69
	s_cselect_b32 s12, s18, s68
	s_add_i32 s68, 0, 0x18000
	v_add_u32_e32 v2, s68, v212
	s_add_i32 s69, 0, 0x1c000
	ds_read_b128 v[146:149], v2
	ds_read_b128 v[150:153], v2 offset:1024
	ds_read_b128 v[154:157], v2 offset:2048
	ds_read_b128 v[158:161], v2 offset:3072
	v_add_u32_e32 v2, s69, v212
	ds_read_b128 v[166:169], v2
	ds_read_b128 v[170:173], v2 offset:1024
	ds_read_b128 v[174:177], v2 offset:2048
	ds_read_b128 v[162:165], v2 offset:3072
	s_mov_b32 m0, s49
	v_lshl_add_u64 v[208:209], v[210:211], 0, s[46:47]
	ds_read_b128 v[2:5], v215 offset:32768
	ds_read_b128 v[6:9], v215 offset:33792
	ds_read_b128 v[180:183], v215 offset:34816
	ds_read_b128 v[184:187], v215 offset:35840
	ds_read_b128 v[216:219], v215 offset:36864
	ds_read_b128 v[220:223], v215 offset:37888
	ds_read_b128 v[224:227], v215 offset:38912
	ds_read_b128 v[228:231], v215 offset:39936
	global_load_lds_dwordx4 v[208:209], off
	v_lshl_add_u64 v[208:209], v[210:211], 0, s[6:7]
	s_mov_b32 m0, s88
	s_nop 0
	global_load_lds_dwordx4 v[208:209], off
	v_lshl_add_u64 v[208:209], s[12:13], 0, v[192:193]
	s_mov_b32 m0, s89
	s_nop 0
	global_load_lds_dword v[208:209], off
	s_waitcnt vmcnt(9)
	s_waitcnt lgkmcnt(0)
	s_setprio 1
	s_barrier
	v_mfma_f32_16x16x32_bf16 v[134:137], v[146:149], v[2:5], v[134:137]
	v_mfma_f32_16x16x32_bf16 v[134:137], v[150:153], v[6:9], v[134:137]
	v_mfma_f32_16x16x32_bf16 v[130:133], v[158:161], v[6:9], v[130:133]
	v_mfma_f32_16x16x32_bf16 v[130:133], v[154:157], v[2:5], v[130:133]
	v_mfma_f32_16x16x32_bf16 v[122:125], v[154:157], v[180:183], v[122:125]
	v_mfma_f32_16x16x32_bf16 v[122:125], v[158:161], v[184:187], v[122:125]
	v_mfma_f32_16x16x32_bf16 v[126:129], v[150:153], v[184:187], v[126:129]
	v_mfma_f32_16x16x32_bf16 v[126:129], v[146:149], v[180:183], v[126:129]
	v_mfma_f32_16x16x32_bf16 v[114:117], v[146:149], v[216:219], v[114:117]
	v_mfma_f32_16x16x32_bf16 v[114:117], v[150:153], v[220:223], v[114:117]
	v_mfma_f32_16x16x32_bf16 v[106:109], v[158:161], v[220:223], v[106:109]
	v_mfma_f32_16x16x32_bf16 v[106:109], v[154:157], v[216:219], v[106:109]
	v_mfma_f32_16x16x32_bf16 v[90:93], v[154:157], v[224:227], v[90:93]
	v_mfma_f32_16x16x32_bf16 v[90:93], v[158:161], v[228:231], v[90:93]
	v_mfma_f32_16x16x32_bf16 v[98:101], v[150:153], v[228:231], v[98:101]
	v_mfma_f32_16x16x32_bf16 v[98:101], v[146:149], v[224:227], v[98:101]
	s_setprio 0
	s_setprio 1
	v_mfma_f32_16x16x32_bf16 v[118:121], v[166:169], v[2:5], v[118:121]
	v_mfma_f32_16x16x32_bf16 v[118:121], v[170:173], v[6:9], v[118:121]
	v_mfma_f32_16x16x32_bf16 v[2:5], v[174:177], v[2:5], v[110:113]
	v_mfma_f32_16x16x32_bf16 v[110:113], v[162:165], v[6:9], v[2:5]
	v_mfma_f32_16x16x32_bf16 v[2:5], v[166:169], v[180:183], v[102:105]
	v_mfma_f32_16x16x32_bf16 v[102:105], v[170:173], v[184:187], v[2:5]
	v_mfma_f32_16x16x32_bf16 v[2:5], v[174:177], v[180:183], v[94:97]
	v_mfma_f32_16x16x32_bf16 v[94:97], v[162:165], v[184:187], v[2:5]
	v_mfma_f32_16x16x32_bf16 v[2:5], v[166:169], v[216:219], v[86:89]
	v_mfma_f32_16x16x32_bf16 v[86:89], v[170:173], v[220:223], v[2:5]
	v_mfma_f32_16x16x32_bf16 v[2:5], v[174:177], v[216:219], v[82:85]
	v_mfma_f32_16x16x32_bf16 v[82:85], v[162:165], v[220:223], v[2:5]
	v_mfma_f32_16x16x32_bf16 v[2:5], v[166:169], v[224:227], v[78:81]
	v_mfma_f32_16x16x32_bf16 v[78:81], v[170:173], v[228:231], v[2:5]
	v_mfma_f32_16x16x32_bf16 v[2:5], v[174:177], v[224:227], v[74:77]
	v_mfma_f32_16x16x32_bf16 v[74:77], v[162:165], v[228:231], v[2:5]
	s_barrier
; #define PG8_SB(B) __builtin_amdgcn_rcpf(1.f + expneg(B))
; #define PG8_SB(B) __builtin_amdgcn_rcpf(1.f + expneg(B))
; #define PG8_STAGE(bufoff, gbase, voff) do { _Pragma("unroll") for (int _i = 0; _i < 2; ++_i) \
;         __builtin_amdgcn_global_load_lds((const unsigned*)((const char*)(gbase) + (size_t)_i * qstep + (voff)[0]), (PG8_LAS unsigned*)(lds + (bufoff) + ldsw + _i * 8192), 16, 0, 0); } while (0)
; #define PG8_LDA(dst, b, h) do { _Pragma("unroll") for (int m = 0; m < 4; ++m) _Pragma("unroll") for (int k = 0; k < 2; ++k) dst[m][k] = *(const PG8_LAS bf16x8*)(lds + PG8_SA(b, h) + aoff + m * 2048 + k * 1024); } while (0)
; #define PG8_MMA(ai, bj, At, Bt) do { __builtin_amdgcn_s_setprio(1); _Pragma("unroll") for (int m = 0; m < 4; ++m) _Pragma("unroll") for (int n = 0; n < 2; ++n) _Pragma("unroll") for (int k = 0; k < 2; ++k) \
;         acc[ai][bj][m][n] = __builtin_amdgcn_mfma_f32_16x16x32_bf16(Bt[n][k], At[m][k], acc[ai][bj][m][n], 0, 0, 0); __builtin_amdgcn_s_setprio(0); } while (0)
; #define PG8_WAIT_V89() do { if constexpr (SLIVER) PG8_WAIT_V(9); else PG8_WAIT_V(8); } while (0)
; #define PG8_LDS_S(b) do { if constexpr (SLIVER) { Sf[0] = *(const PG8_LAS bf16x8*)(lds + STAGE_BYTES + (b) * 2048 + soff0); Sf[1] = *(const PG8_LAS bf16x8*)(lds + STAGE_BYTES + (b) * 2048 + (soff0 ^ 64)); } } while (0)
; #define PG8_WAIT_L(n) asm volatile("s_waitcnt lgkmcnt(" #n ")" ::: "memory")
; #define PG8_BAR __builtin_amdgcn_s_barrier()
; #define PG8_SCHED __builtin_amdgcn_sched_barrier(0)
; template <class Epi, class Sched, bool ALIGN_EPI = false, bool SP2 = false, bool SLIVER = false>
; __device__ __forceinline__ void gemm_phase(PG8_LAS unsigned char* lds, const Gemm g, const Sched& S, const Epi& E) {
;     ...
;             PG8_LDA(At, 1, 1); PG8_LDS_S(1); PG8_STAGE(PG8_SB(1, 0), b3, voffB); PG8_STAGE(PG8_SB(1, 1), b3 + hstep, voffB); PG8_STAGE(PG8_SA(1, 0), a3, voffA);
;             PG8_WAIT_V89(); PG8_WAIT_L(0); PG8_BAR; PG8_MMA(1, 0, At, B0); PG8_MMA(1, 1, At, B1); PG8_MMA_S(); PG8_BAR; PG8_SCHED;
	s_setprio 0
	s_add_i32 s12, 0, 0x20800
	v_add_u32_e32 v178, s12, v213
	v_add_u32_e32 v184, s12, v214
	s_add_i32 s12, s68, s92
	v_lshl_add_u64 v[208:209], v[202:203], 0, s[26:27]
	s_mov_b32 m0, s12
	ds_read_b128 v[2:5], v215 offset:49152
	ds_read_b128 v[6:9], v215 offset:50176
	ds_read_b128 v[216:219], v215 offset:51200
	ds_read_b128 v[220:223], v215 offset:52224
	ds_read_b128 v[224:227], v215 offset:53248
	ds_read_b128 v[228:231], v215 offset:54272
	ds_read_b128 v[232:235], v215 offset:55296
	ds_read_b128 v[240:243], v215 offset:56320
	ds_read_b128 v[180:183], v178
	ds_read_b128 v[184:187], v184
	global_load_lds_dwordx4 v[208:209], off
	v_lshl_add_u64 v[208:209], v[202:203], 0, s[58:59]
	s_add_i32 m0, s12, 0x2000
	s_mov_b64 s[12:13], 0x90080
	global_load_lds_dwordx4 v[208:209], off
	v_lshl_add_u64 v[208:209], v[202:203], 0, s[12:13]
	s_add_i32 s12, s69, s92
	s_mov_b32 m0, s12
	s_mov_b64 s[68:69], 0xd8080
	global_load_lds_dwordx4 v[208:209], off
	v_lshl_add_u64 v[202:203], v[202:203], 0, s[68:69]
	s_add_i32 m0, s12, 0x2000
	s_nop 0
	global_load_lds_dwordx4 v[202:203], off
	v_lshl_add_u64 v[202:203], v[210:211], 0, s[26:27]
	s_mov_b32 m0, s51
	s_nop 0
	global_load_lds_dwordx4 v[202:203], off
	v_lshl_add_u64 v[202:203], v[210:211], 0, s[58:59]
	s_mov_b32 m0, s53
	s_nop 0
	global_load_lds_dwordx4 v[202:203], off
	s_waitcnt vmcnt(9)
	s_waitcnt lgkmcnt(0)
	s_setprio 1
	s_barrier
	v_mfma_f32_16x16x32_bf16 v[70:73], v[146:149], v[2:5], v[70:73]
	v_mfma_f32_16x16x32_bf16 v[70:73], v[150:153], v[6:9], v[70:73]
	v_mfma_f32_16x16x32_bf16 v[66:69], v[158:161], v[6:9], v[66:69]
	v_mfma_f32_16x16x32_bf16 v[66:69], v[154:157], v[2:5], v[66:69]
	v_mfma_f32_16x16x32_bf16 v[58:61], v[154:157], v[216:219], v[58:61]
	v_mfma_f32_16x16x32_bf16 v[58:61], v[158:161], v[220:223], v[58:61]
	v_mfma_f32_16x16x32_bf16 v[62:65], v[150:153], v[220:223], v[62:65]
	v_mfma_f32_16x16x32_bf16 v[62:65], v[146:149], v[216:219], v[62:65]
	v_mfma_f32_16x16x32_bf16 v[50:53], v[146:149], v[224:227], v[50:53]
	v_mfma_f32_16x16x32_bf16 v[50:53], v[150:153], v[228:231], v[50:53]
	v_mfma_f32_16x16x32_bf16 v[42:45], v[158:161], v[228:231], v[42:45]
	v_mfma_f32_16x16x32_bf16 v[42:45], v[154:157], v[224:227], v[42:45]
	v_mfma_f32_16x16x32_bf16 v[26:29], v[154:157], v[232:235], v[26:29]
	v_mfma_f32_16x16x32_bf16 v[26:29], v[158:161], v[240:243], v[26:29]
	v_mfma_f32_16x16x32_bf16 v[34:37], v[150:153], v[240:243], v[34:37]
	v_mfma_f32_16x16x32_bf16 v[34:37], v[146:149], v[232:235], v[34:37]
	s_setprio 0
	s_setprio 1
	v_mfma_f32_16x16x32_bf16 v[54:57], v[166:169], v[2:5], v[54:57]
	v_mfma_f32_16x16x32_bf16 v[54:57], v[170:173], v[6:9], v[54:57]
	v_mfma_f32_16x16x32_bf16 v[2:5], v[174:177], v[2:5], v[46:49]
	v_mfma_f32_16x16x32_bf16 v[46:49], v[162:165], v[6:9], v[2:5]
	v_mfma_f32_16x16x32_bf16 v[2:5], v[166:169], v[216:219], v[38:41]
	v_mfma_f32_16x16x32_bf16 v[38:41], v[170:173], v[220:223], v[2:5]
	v_mfma_f32_16x16x32_bf16 v[2:5], v[174:177], v[216:219], v[30:33]
	v_mfma_f32_16x16x32_bf16 v[30:33], v[162:165], v[220:223], v[2:5]
	v_mfma_f32_16x16x32_bf16 v[2:5], v[166:169], v[224:227], v[22:25]
	v_mfma_f32_16x16x32_bf16 v[22:25], v[170:173], v[228:231], v[2:5]
	v_mfma_f32_16x16x32_bf16 v[2:5], v[174:177], v[224:227], v[18:21]
	v_mfma_f32_16x16x32_bf16 v[18:21], v[162:165], v[228:231], v[2:5]
	v_mfma_f32_16x16x32_bf16 v[2:5], v[166:169], v[232:235], v[14:17]
	v_mfma_f32_16x16x32_bf16 v[14:17], v[170:173], v[240:243], v[2:5]
	v_mfma_f32_16x16x32_bf16 v[2:5], v[174:177], v[232:235], v[10:13]
	v_mfma_f32_16x16x32_bf16 v[10:13], v[162:165], v[240:243], v[2:5]
	s_setprio 0
	s_setprio 1
	s_and_b64 vcc, exec, s[90:91]
	s_cbranch_vccz .Lslv_c3
	v_mfma_f32_16x16x32_bf16 v[2:5], v[166:169], v[180:183], v[138:141]
	v_mfma_f32_16x16x32_bf16 v[6:9], v[170:173], v[184:187], v[2:5]
	v_mfma_f32_16x16x32_bf16 v[2:5], v[162:165], v[184:187], v[142:145]
	v_mfma_f32_16x16x32_bf16 v[2:5], v[174:177], v[180:183], v[2:5]
	s_branch .LBB0_933
